# hyconv Toeplitz ladders: shared B fragment double-buffered (read one step of 8 MFMAs ahead) on top of the attention LDS-DMA version
# baseline (speedup 1.0000x reference)
.LBB0_800:
	s_or_b64 exec, exec, s[0:1]
	ds_read_b128 v[6:9], v97 offset:4064
	ds_read_b128 v[10:13], v97 offset:4000
	ds_read_b128 v[38:41], v149
	ds_read_b128 v[34:37], v97 offset:3680
	ds_read_b128 v[66:69], v97 offset:3616
	ds_read_b128 v[18:21], v97 offset:3936
	ds_read_b128 v[22:25], v97 offset:3872
	ds_read_b128 v[26:29], v97 offset:3808
	ds_read_b128 v[30:33], v97 offset:3744
	ds_read_b128 v[14:17], v97 offset:4128
	ds_read_b128 v[70:73], v150
	s_waitcnt lgkmcnt(7)
	v_mfma_f32_16x16x32_bf16 v[74:77], v[34:37], v[38:41], 0
	s_add_i32 s0, s24, 0x800
	s_mul_hi_i32 s1, s0, 0xc000
	s_mul_i32 s0, s0, 0xc000
	v_mfma_f32_16x16x32_bf16 v[42:45], v[6:9], v[38:41], 0
	s_add_u32 s2, s20, s0
	s_addc_u32 s3, s68, s1
	v_mov_b32_e32 v137, 0
	v_mfma_f32_16x16x32_bf16 v[46:49], v[10:13], v[38:41], 0
	s_waitcnt lgkmcnt(5)
	v_mfma_f32_16x16x32_bf16 v[50:53], v[18:21], v[38:41], 0
	s_waitcnt lgkmcnt(4)
	v_mfma_f32_16x16x32_bf16 v[54:57], v[22:25], v[38:41], 0
	s_waitcnt lgkmcnt(3)
	v_mfma_f32_16x16x32_bf16 v[58:61], v[26:29], v[38:41], 0
	s_waitcnt lgkmcnt(2)
	v_mfma_f32_16x16x32_bf16 v[62:65], v[30:33], v[38:41], 0
	v_mfma_f32_16x16x32_bf16 v[38:41], v[66:69], v[38:41], 0
	s_waitcnt lgkmcnt(0)
	v_mfma_f32_16x16x32_bf16 v[66:69], v[30:33], v[70:73], v[74:77]
	s_nop 2
	ds_read_b128 v[74:77], v97 offset:4192
	v_mfma_f32_16x16x32_bf16 v[34:37], v[34:37], v[70:73], v[38:41]
	s_nop 2
	ds_read_b128 v[38:41], v150 offset:64
	v_mfma_f32_16x16x32_bf16 v[42:45], v[14:17], v[70:73], v[42:45]
	v_mfma_f32_16x16x32_bf16 v[46:49], v[6:9], v[70:73], v[46:49]
	v_mfma_f32_16x16x32_bf16 v[50:53], v[10:13], v[70:73], v[50:53]
	v_mfma_f32_16x16x32_bf16 v[54:57], v[18:21], v[70:73], v[54:57]
	v_mfma_f32_16x16x32_bf16 v[58:61], v[22:25], v[70:73], v[58:61]
	v_mfma_f32_16x16x32_bf16 v[62:65], v[26:29], v[70:73], v[62:65]
	ds_read_b128 v[70:73], v97 offset:4256
	s_waitcnt lgkmcnt(1)
	v_mfma_f32_16x16x32_bf16 v[30:33], v[30:33], v[38:41], v[34:37]
	s_nop 2
	ds_read_b128 v[34:37], v150 offset:128
	v_mfma_f32_16x16x32_bf16 v[42:45], v[74:77], v[38:41], v[42:45]
	v_mfma_f32_16x16x32_bf16 v[46:49], v[14:17], v[38:41], v[46:49]
	v_mfma_f32_16x16x32_bf16 v[50:53], v[6:9], v[38:41], v[50:53]
	v_mfma_f32_16x16x32_bf16 v[54:57], v[10:13], v[38:41], v[54:57]
	v_mfma_f32_16x16x32_bf16 v[58:61], v[18:21], v[38:41], v[58:61]
	v_mfma_f32_16x16x32_bf16 v[62:65], v[22:25], v[38:41], v[62:65]
	v_mfma_f32_16x16x32_bf16 v[66:69], v[26:29], v[38:41], v[66:69]
	s_waitcnt lgkmcnt(0)
	v_mfma_f32_16x16x32_bf16 v[38:41], v[70:73], v[34:37], v[42:45]
	v_mfma_f32_16x16x32_bf16 v[42:45], v[74:77], v[34:37], v[46:49]
	v_mfma_f32_16x16x32_bf16 v[46:49], v[14:17], v[34:37], v[50:53]
	v_mfma_f32_16x16x32_bf16 v[50:53], v[6:9], v[34:37], v[54:57]
	v_mfma_f32_16x16x32_bf16 v[54:57], v[10:13], v[34:37], v[58:61]
	v_mfma_f32_16x16x32_bf16 v[58:61], v[18:21], v[34:37], v[62:65]
	v_mfma_f32_16x16x32_bf16 v[62:65], v[22:25], v[34:37], v[66:69]
	s_nop 2
	ds_read_b128 v[66:69], v97 offset:4320
	v_mfma_f32_16x16x32_bf16 v[26:29], v[26:29], v[34:37], v[30:33]
	s_nop 2
	ds_read_b128 v[30:33], v150 offset:192
	s_waitcnt lgkmcnt(0)
	v_mfma_f32_16x16x32_bf16 v[34:37], v[66:69], v[30:33], v[38:41]
	v_mfma_f32_16x16x32_bf16 v[38:41], v[70:73], v[30:33], v[42:45]
	v_mfma_f32_16x16x32_bf16 v[42:45], v[74:77], v[30:33], v[46:49]
	v_mfma_f32_16x16x32_bf16 v[46:49], v[14:17], v[30:33], v[50:53]
	v_mfma_f32_16x16x32_bf16 v[50:53], v[6:9], v[30:33], v[54:57]
	v_mfma_f32_16x16x32_bf16 v[54:57], v[10:13], v[30:33], v[58:61]
	v_mfma_f32_16x16x32_bf16 v[58:61], v[18:21], v[30:33], v[62:65]
	s_nop 2
	ds_read_b128 v[62:65], v97 offset:4384
	v_mfma_f32_16x16x32_bf16 v[22:25], v[22:25], v[30:33], v[26:29]
	s_nop 2
	ds_read_b128 v[26:29], v150 offset:256
	s_waitcnt lgkmcnt(0)
	v_mfma_f32_16x16x32_bf16 v[30:33], v[62:65], v[26:29], v[34:37]
	v_mfma_f32_16x16x32_bf16 v[34:37], v[66:69], v[26:29], v[38:41]
	v_mfma_f32_16x16x32_bf16 v[38:41], v[70:73], v[26:29], v[42:45]
	v_mfma_f32_16x16x32_bf16 v[42:45], v[74:77], v[26:29], v[46:49]
	v_mfma_f32_16x16x32_bf16 v[46:49], v[14:17], v[26:29], v[50:53]
	v_mfma_f32_16x16x32_bf16 v[50:53], v[6:9], v[26:29], v[54:57]
	v_mfma_f32_16x16x32_bf16 v[54:57], v[10:13], v[26:29], v[58:61]
	s_nop 2
	ds_read_b128 v[58:61], v97 offset:4448
	v_mfma_f32_16x16x32_bf16 v[18:21], v[18:21], v[26:29], v[22:25]
	s_nop 2
	ds_read_b128 v[22:25], v150 offset:320
	s_waitcnt lgkmcnt(0)
	v_mfma_f32_16x16x32_bf16 v[26:29], v[58:61], v[22:25], v[30:33]
	v_mfma_f32_16x16x32_bf16 v[30:33], v[62:65], v[22:25], v[34:37]
	v_mfma_f32_16x16x32_bf16 v[34:37], v[66:69], v[22:25], v[38:41]
	v_mfma_f32_16x16x32_bf16 v[38:41], v[70:73], v[22:25], v[42:45]
	v_mfma_f32_16x16x32_bf16 v[42:45], v[74:77], v[22:25], v[46:49]
	v_mfma_f32_16x16x32_bf16 v[46:49], v[14:17], v[22:25], v[50:53]
	v_mfma_f32_16x16x32_bf16 v[50:53], v[6:9], v[22:25], v[54:57]
	s_nop 2
	ds_read_b128 v[54:57], v97 offset:4512
	v_mfma_f32_16x16x32_bf16 v[10:13], v[10:13], v[22:25], v[18:21]
	s_nop 2
	ds_read_b128 v[18:21], v150 offset:384
	s_waitcnt lgkmcnt(0)
	v_mfma_f32_16x16x32_bf16 v[22:25], v[54:57], v[18:21], v[26:29]
	v_mfma_f32_16x16x32_bf16 v[26:29], v[58:61], v[18:21], v[30:33]
	v_mfma_f32_16x16x32_bf16 v[30:33], v[62:65], v[18:21], v[34:37]
	v_mfma_f32_16x16x32_bf16 v[34:37], v[66:69], v[18:21], v[38:41]
	v_mfma_f32_16x16x32_bf16 v[38:41], v[70:73], v[18:21], v[42:45]
	v_mfma_f32_16x16x32_bf16 v[42:45], v[74:77], v[18:21], v[46:49]
	v_mfma_f32_16x16x32_bf16 v[46:49], v[14:17], v[18:21], v[50:53]
	s_nop 2
	ds_read_b128 v[50:53], v97 offset:4576
	v_mfma_f32_16x16x32_bf16 v[6:9], v[6:9], v[18:21], v[10:13]
	s_nop 2
	ds_read_b128 v[10:13], v150 offset:448
	s_waitcnt lgkmcnt(0)
	v_mfma_f32_16x16x32_bf16 v[18:21], v[50:53], v[10:13], v[22:25]
	v_mfma_f32_16x16x32_bf16 v[22:25], v[54:57], v[10:13], v[26:29]
	v_mfma_f32_16x16x32_bf16 v[26:29], v[58:61], v[10:13], v[30:33]
	v_mfma_f32_16x16x32_bf16 v[30:33], v[62:65], v[10:13], v[34:37]
	v_mfma_f32_16x16x32_bf16 v[34:37], v[66:69], v[10:13], v[38:41]
	v_mfma_f32_16x16x32_bf16 v[38:41], v[70:73], v[10:13], v[42:45]
	v_mfma_f32_16x16x32_bf16 v[42:45], v[74:77], v[10:13], v[46:49]
	s_nop 2
	ds_read_b128 v[46:49], v97 offset:4640
	v_mfma_f32_16x16x32_bf16 v[6:9], v[14:17], v[10:13], v[6:9]
	ds_read_b128 v[10:13], v150 offset:512
	s_waitcnt lgkmcnt(0)
	v_mfma_f32_16x16x32_bf16 v[6:9], v[74:77], v[10:13], v[6:9]
	ds_read_b128 v[74:77], v97 offset:4768
	v_mfma_f32_16x16x32_bf16 v[14:17], v[46:49], v[10:13], v[18:21]
	v_mfma_f32_16x16x32_bf16 v[18:21], v[50:53], v[10:13], v[22:25]
	v_mfma_f32_16x16x32_bf16 v[22:25], v[54:57], v[10:13], v[26:29]
	v_mfma_f32_16x16x32_bf16 v[26:29], v[58:61], v[10:13], v[30:33]
	v_mfma_f32_16x16x32_bf16 v[30:33], v[62:65], v[10:13], v[34:37]
	v_mfma_f32_16x16x32_bf16 v[34:37], v[66:69], v[10:13], v[38:41]
	v_mfma_f32_16x16x32_bf16 v[38:41], v[70:73], v[10:13], v[42:45]
	ds_read_b128 v[10:13], v150 offset:576
	s_nop 1
	ds_read_b128 v[42:45], v97 offset:4704
	s_waitcnt lgkmcnt(1)
	v_mfma_f32_16x16x32_bf16 v[18:21], v[46:49], v[10:13], v[18:21]
	v_mfma_f32_16x16x32_bf16 v[22:25], v[50:53], v[10:13], v[22:25]
	v_mfma_f32_16x16x32_bf16 v[26:29], v[54:57], v[10:13], v[26:29]
	v_mfma_f32_16x16x32_bf16 v[30:33], v[58:61], v[10:13], v[30:33]
	v_mfma_f32_16x16x32_bf16 v[34:37], v[62:65], v[10:13], v[34:37]
	v_mfma_f32_16x16x32_bf16 v[38:41], v[66:69], v[10:13], v[38:41]
	v_mfma_f32_16x16x32_bf16 v[6:9], v[70:73], v[10:13], v[6:9]
	ds_read_b128 v[70:73], v97 offset:4832
	s_waitcnt lgkmcnt(1)
	v_mfma_f32_16x16x32_bf16 v[14:17], v[42:45], v[10:13], v[14:17]
	ds_read_b128 v[10:13], v150 offset:640
	s_waitcnt lgkmcnt(0)
	ds_read_b128 v[238:241], v150 offset:704
	v_mfma_f32_16x16x32_bf16 v[14:17], v[74:77], v[10:13], v[14:17]
	v_mfma_f32_16x16x32_bf16 v[18:21], v[42:45], v[10:13], v[18:21]
	v_mfma_f32_16x16x32_bf16 v[22:25], v[46:49], v[10:13], v[22:25]
	v_mfma_f32_16x16x32_bf16 v[26:29], v[50:53], v[10:13], v[26:29]
	v_mfma_f32_16x16x32_bf16 v[30:33], v[54:57], v[10:13], v[30:33]
	v_mfma_f32_16x16x32_bf16 v[34:37], v[58:61], v[10:13], v[34:37]
	v_mfma_f32_16x16x32_bf16 v[38:41], v[62:65], v[10:13], v[38:41]
	v_mfma_f32_16x16x32_bf16 v[6:9], v[66:69], v[10:13], v[6:9]
	ds_read_b128 v[10:13], v150 offset:768
	ds_read_b128 v[66:69], v97 offset:4896
	s_waitcnt lgkmcnt(2)
	v_mfma_f32_16x16x32_bf16 v[14:17], v[70:73], v[238:241], v[14:17]
	v_mfma_f32_16x16x32_bf16 v[18:21], v[74:77], v[238:241], v[18:21]
	v_mfma_f32_16x16x32_bf16 v[22:25], v[42:45], v[238:241], v[22:25]
	v_mfma_f32_16x16x32_bf16 v[26:29], v[46:49], v[238:241], v[26:29]
	v_mfma_f32_16x16x32_bf16 v[30:33], v[50:53], v[238:241], v[30:33]
	v_mfma_f32_16x16x32_bf16 v[34:37], v[54:57], v[238:241], v[34:37]
	v_mfma_f32_16x16x32_bf16 v[38:41], v[58:61], v[238:241], v[38:41]
	v_mfma_f32_16x16x32_bf16 v[6:9], v[62:65], v[238:241], v[6:9]
	ds_read_b128 v[238:241], v150 offset:832
	ds_read_b128 v[62:65], v97 offset:4960
	s_waitcnt lgkmcnt(2)
	v_mfma_f32_16x16x32_bf16 v[14:17], v[66:69], v[10:13], v[14:17]
	v_mfma_f32_16x16x32_bf16 v[18:21], v[70:73], v[10:13], v[18:21]
	v_mfma_f32_16x16x32_bf16 v[22:25], v[74:77], v[10:13], v[22:25]
	v_mfma_f32_16x16x32_bf16 v[26:29], v[42:45], v[10:13], v[26:29]
	v_mfma_f32_16x16x32_bf16 v[30:33], v[46:49], v[10:13], v[30:33]
	v_mfma_f32_16x16x32_bf16 v[34:37], v[50:53], v[10:13], v[34:37]
	v_mfma_f32_16x16x32_bf16 v[38:41], v[54:57], v[10:13], v[38:41]
	v_mfma_f32_16x16x32_bf16 v[6:9], v[58:61], v[10:13], v[6:9]
	ds_read_b128 v[10:13], v150 offset:896
	ds_read_b128 v[58:61], v97 offset:5024
	s_waitcnt lgkmcnt(2)
	v_mfma_f32_16x16x32_bf16 v[14:17], v[62:65], v[238:241], v[14:17]
	v_mfma_f32_16x16x32_bf16 v[18:21], v[66:69], v[238:241], v[18:21]
	v_mfma_f32_16x16x32_bf16 v[22:25], v[70:73], v[238:241], v[22:25]
	v_mfma_f32_16x16x32_bf16 v[26:29], v[74:77], v[238:241], v[26:29]
	v_mfma_f32_16x16x32_bf16 v[30:33], v[42:45], v[238:241], v[30:33]
	v_mfma_f32_16x16x32_bf16 v[34:37], v[46:49], v[238:241], v[34:37]
	v_mfma_f32_16x16x32_bf16 v[38:41], v[50:53], v[238:241], v[38:41]
	v_mfma_f32_16x16x32_bf16 v[6:9], v[54:57], v[238:241], v[6:9]
	ds_read_b128 v[238:241], v150 offset:960
	ds_read_b128 v[54:57], v97 offset:5088
	s_waitcnt lgkmcnt(2)
	v_mfma_f32_16x16x32_bf16 v[14:17], v[58:61], v[10:13], v[14:17]
	v_mfma_f32_16x16x32_bf16 v[18:21], v[62:65], v[10:13], v[18:21]
	v_mfma_f32_16x16x32_bf16 v[22:25], v[66:69], v[10:13], v[22:25]
	v_mfma_f32_16x16x32_bf16 v[26:29], v[70:73], v[10:13], v[26:29]
	v_mfma_f32_16x16x32_bf16 v[30:33], v[74:77], v[10:13], v[30:33]
	v_mfma_f32_16x16x32_bf16 v[34:37], v[42:45], v[10:13], v[34:37]
	v_mfma_f32_16x16x32_bf16 v[38:41], v[46:49], v[10:13], v[38:41]
	v_mfma_f32_16x16x32_bf16 v[6:9], v[50:53], v[10:13], v[6:9]
	ds_read_b128 v[10:13], v150 offset:1024
	ds_read_b128 v[50:53], v97 offset:5152
	s_waitcnt lgkmcnt(2)
	v_mfma_f32_16x16x32_bf16 v[14:17], v[54:57], v[238:241], v[14:17]
	v_mfma_f32_16x16x32_bf16 v[18:21], v[58:61], v[238:241], v[18:21]
	v_mfma_f32_16x16x32_bf16 v[22:25], v[62:65], v[238:241], v[22:25]
	v_mfma_f32_16x16x32_bf16 v[26:29], v[66:69], v[238:241], v[26:29]
	v_mfma_f32_16x16x32_bf16 v[30:33], v[70:73], v[238:241], v[30:33]
	v_mfma_f32_16x16x32_bf16 v[34:37], v[74:77], v[238:241], v[34:37]
	v_mfma_f32_16x16x32_bf16 v[38:41], v[42:45], v[238:241], v[38:41]
	v_mfma_f32_16x16x32_bf16 v[6:9], v[46:49], v[238:241], v[6:9]
	ds_read_b128 v[238:241], v150 offset:1088
	ds_read_b128 v[46:49], v97 offset:5216
	s_waitcnt lgkmcnt(2)
	v_mfma_f32_16x16x32_bf16 v[14:17], v[50:53], v[10:13], v[14:17]
	v_mfma_f32_16x16x32_bf16 v[18:21], v[54:57], v[10:13], v[18:21]
	v_mfma_f32_16x16x32_bf16 v[22:25], v[58:61], v[10:13], v[22:25]
	v_mfma_f32_16x16x32_bf16 v[26:29], v[62:65], v[10:13], v[26:29]
	v_mfma_f32_16x16x32_bf16 v[30:33], v[66:69], v[10:13], v[30:33]
	v_mfma_f32_16x16x32_bf16 v[34:37], v[70:73], v[10:13], v[34:37]
	v_mfma_f32_16x16x32_bf16 v[38:41], v[74:77], v[10:13], v[38:41]
	v_mfma_f32_16x16x32_bf16 v[6:9], v[42:45], v[10:13], v[6:9]
	ds_read_b128 v[10:13], v150 offset:1152
	ds_read_b128 v[42:45], v97 offset:5280
	s_waitcnt lgkmcnt(2)
	v_mfma_f32_16x16x32_bf16 v[14:17], v[46:49], v[238:241], v[14:17]
	v_mfma_f32_16x16x32_bf16 v[18:21], v[50:53], v[238:241], v[18:21]
	v_mfma_f32_16x16x32_bf16 v[22:25], v[54:57], v[238:241], v[22:25]
	v_mfma_f32_16x16x32_bf16 v[26:29], v[58:61], v[238:241], v[26:29]
	v_mfma_f32_16x16x32_bf16 v[30:33], v[62:65], v[238:241], v[30:33]
	v_mfma_f32_16x16x32_bf16 v[34:37], v[66:69], v[238:241], v[34:37]
	v_mfma_f32_16x16x32_bf16 v[38:41], v[70:73], v[238:241], v[38:41]
	v_mfma_f32_16x16x32_bf16 v[6:9], v[74:77], v[238:241], v[6:9]
	ds_read_b128 v[238:241], v150 offset:1216
	ds_read_b128 v[74:77], v97 offset:5344
	s_waitcnt lgkmcnt(2)
	v_mfma_f32_16x16x32_bf16 v[14:17], v[42:45], v[10:13], v[14:17]
	v_mfma_f32_16x16x32_bf16 v[18:21], v[46:49], v[10:13], v[18:21]
	v_mfma_f32_16x16x32_bf16 v[22:25], v[50:53], v[10:13], v[22:25]
	v_mfma_f32_16x16x32_bf16 v[26:29], v[54:57], v[10:13], v[26:29]
	v_mfma_f32_16x16x32_bf16 v[30:33], v[58:61], v[10:13], v[30:33]
	v_mfma_f32_16x16x32_bf16 v[34:37], v[62:65], v[10:13], v[34:37]
	v_mfma_f32_16x16x32_bf16 v[38:41], v[66:69], v[10:13], v[38:41]
	v_mfma_f32_16x16x32_bf16 v[6:9], v[70:73], v[10:13], v[6:9]
	ds_read_b128 v[10:13], v150 offset:1280
	ds_read_b128 v[70:73], v97 offset:5408
	s_waitcnt lgkmcnt(2)
	v_mfma_f32_16x16x32_bf16 v[14:17], v[74:77], v[238:241], v[14:17]
	v_mfma_f32_16x16x32_bf16 v[18:21], v[42:45], v[238:241], v[18:21]
	v_mfma_f32_16x16x32_bf16 v[22:25], v[46:49], v[238:241], v[22:25]
	v_mfma_f32_16x16x32_bf16 v[26:29], v[50:53], v[238:241], v[26:29]
	v_mfma_f32_16x16x32_bf16 v[30:33], v[54:57], v[238:241], v[30:33]
	v_mfma_f32_16x16x32_bf16 v[34:37], v[58:61], v[238:241], v[34:37]
	v_mfma_f32_16x16x32_bf16 v[38:41], v[62:65], v[238:241], v[38:41]
	v_mfma_f32_16x16x32_bf16 v[6:9], v[66:69], v[238:241], v[6:9]
	ds_read_b128 v[238:241], v150 offset:1344
	ds_read_b128 v[66:69], v97 offset:5472
	s_waitcnt lgkmcnt(2)
	v_mfma_f32_16x16x32_bf16 v[14:17], v[70:73], v[10:13], v[14:17]
	v_mfma_f32_16x16x32_bf16 v[18:21], v[74:77], v[10:13], v[18:21]
	v_mfma_f32_16x16x32_bf16 v[22:25], v[42:45], v[10:13], v[22:25]
	v_mfma_f32_16x16x32_bf16 v[26:29], v[46:49], v[10:13], v[26:29]
	v_mfma_f32_16x16x32_bf16 v[30:33], v[50:53], v[10:13], v[30:33]
	v_mfma_f32_16x16x32_bf16 v[34:37], v[54:57], v[10:13], v[34:37]
	v_mfma_f32_16x16x32_bf16 v[38:41], v[58:61], v[10:13], v[38:41]
	v_mfma_f32_16x16x32_bf16 v[6:9], v[62:65], v[10:13], v[6:9]
	ds_read_b128 v[10:13], v150 offset:1408
	ds_read_b128 v[62:65], v97 offset:5536
	s_waitcnt lgkmcnt(2)
	v_mfma_f32_16x16x32_bf16 v[14:17], v[66:69], v[238:241], v[14:17]
	v_mfma_f32_16x16x32_bf16 v[18:21], v[70:73], v[238:241], v[18:21]
	v_mfma_f32_16x16x32_bf16 v[22:25], v[74:77], v[238:241], v[22:25]
	v_mfma_f32_16x16x32_bf16 v[26:29], v[42:45], v[238:241], v[26:29]
	v_mfma_f32_16x16x32_bf16 v[30:33], v[46:49], v[238:241], v[30:33]
	v_mfma_f32_16x16x32_bf16 v[34:37], v[50:53], v[238:241], v[34:37]
	v_mfma_f32_16x16x32_bf16 v[38:41], v[54:57], v[238:241], v[38:41]
	v_mfma_f32_16x16x32_bf16 v[6:9], v[58:61], v[238:241], v[6:9]
	ds_read_b128 v[238:241], v150 offset:1472
	ds_read_b128 v[58:61], v97 offset:5600
	s_waitcnt lgkmcnt(2)
	v_mfma_f32_16x16x32_bf16 v[14:17], v[62:65], v[10:13], v[14:17]
	v_mfma_f32_16x16x32_bf16 v[18:21], v[66:69], v[10:13], v[18:21]
	v_mfma_f32_16x16x32_bf16 v[22:25], v[70:73], v[10:13], v[22:25]
	v_mfma_f32_16x16x32_bf16 v[26:29], v[74:77], v[10:13], v[26:29]
	v_mfma_f32_16x16x32_bf16 v[30:33], v[42:45], v[10:13], v[30:33]
	v_mfma_f32_16x16x32_bf16 v[34:37], v[46:49], v[10:13], v[34:37]
	v_mfma_f32_16x16x32_bf16 v[38:41], v[50:53], v[10:13], v[38:41]
	v_mfma_f32_16x16x32_bf16 v[6:9], v[54:57], v[10:13], v[6:9]
	ds_read_b128 v[10:13], v150 offset:1536
	ds_read_b128 v[54:57], v97 offset:5664
	s_waitcnt lgkmcnt(2)
	v_mfma_f32_16x16x32_bf16 v[14:17], v[58:61], v[238:241], v[14:17]
	v_mfma_f32_16x16x32_bf16 v[18:21], v[62:65], v[238:241], v[18:21]
	v_mfma_f32_16x16x32_bf16 v[22:25], v[66:69], v[238:241], v[22:25]
	v_mfma_f32_16x16x32_bf16 v[26:29], v[70:73], v[238:241], v[26:29]
	v_mfma_f32_16x16x32_bf16 v[30:33], v[74:77], v[238:241], v[30:33]
	v_mfma_f32_16x16x32_bf16 v[34:37], v[42:45], v[238:241], v[34:37]
	v_mfma_f32_16x16x32_bf16 v[38:41], v[46:49], v[238:241], v[38:41]
	v_mfma_f32_16x16x32_bf16 v[6:9], v[50:53], v[238:241], v[6:9]
	ds_read_b128 v[238:241], v150 offset:1600
	ds_read_b128 v[50:53], v97 offset:5728
	s_waitcnt lgkmcnt(2)
	v_mfma_f32_16x16x32_bf16 v[14:17], v[54:57], v[10:13], v[14:17]
	v_mfma_f32_16x16x32_bf16 v[18:21], v[58:61], v[10:13], v[18:21]
	v_mfma_f32_16x16x32_bf16 v[22:25], v[62:65], v[10:13], v[22:25]
	v_mfma_f32_16x16x32_bf16 v[26:29], v[66:69], v[10:13], v[26:29]
	v_mfma_f32_16x16x32_bf16 v[30:33], v[70:73], v[10:13], v[30:33]
	v_mfma_f32_16x16x32_bf16 v[34:37], v[74:77], v[10:13], v[34:37]
	v_mfma_f32_16x16x32_bf16 v[38:41], v[42:45], v[10:13], v[38:41]
	v_mfma_f32_16x16x32_bf16 v[6:9], v[46:49], v[10:13], v[6:9]
	ds_read_b128 v[10:13], v150 offset:1664
	ds_read_b128 v[46:49], v97 offset:5792
	s_waitcnt lgkmcnt(2)
	v_mfma_f32_16x16x32_bf16 v[14:17], v[50:53], v[238:241], v[14:17]
	v_mfma_f32_16x16x32_bf16 v[18:21], v[54:57], v[238:241], v[18:21]
	v_mfma_f32_16x16x32_bf16 v[22:25], v[58:61], v[238:241], v[22:25]
	v_mfma_f32_16x16x32_bf16 v[26:29], v[62:65], v[238:241], v[26:29]
	v_mfma_f32_16x16x32_bf16 v[30:33], v[66:69], v[238:241], v[30:33]
	v_mfma_f32_16x16x32_bf16 v[34:37], v[70:73], v[238:241], v[34:37]
	v_mfma_f32_16x16x32_bf16 v[38:41], v[74:77], v[238:241], v[38:41]
	v_mfma_f32_16x16x32_bf16 v[6:9], v[42:45], v[238:241], v[6:9]
	ds_read_b128 v[238:241], v150 offset:1728
	ds_read_b128 v[42:45], v97 offset:5856
	s_waitcnt lgkmcnt(2)
	v_mfma_f32_16x16x32_bf16 v[14:17], v[46:49], v[10:13], v[14:17]
	v_mfma_f32_16x16x32_bf16 v[18:21], v[50:53], v[10:13], v[18:21]
	v_mfma_f32_16x16x32_bf16 v[22:25], v[54:57], v[10:13], v[22:25]
	v_mfma_f32_16x16x32_bf16 v[26:29], v[58:61], v[10:13], v[26:29]
	v_mfma_f32_16x16x32_bf16 v[30:33], v[62:65], v[10:13], v[30:33]
	v_mfma_f32_16x16x32_bf16 v[34:37], v[66:69], v[10:13], v[34:37]
	v_mfma_f32_16x16x32_bf16 v[38:41], v[70:73], v[10:13], v[38:41]
	v_mfma_f32_16x16x32_bf16 v[6:9], v[74:77], v[10:13], v[6:9]
	ds_read_b128 v[10:13], v150 offset:1792
	ds_read_b128 v[74:77], v97 offset:5920
	s_waitcnt lgkmcnt(2)
	v_mfma_f32_16x16x32_bf16 v[14:17], v[42:45], v[238:241], v[14:17]
	v_mfma_f32_16x16x32_bf16 v[18:21], v[46:49], v[238:241], v[18:21]
	v_mfma_f32_16x16x32_bf16 v[22:25], v[50:53], v[238:241], v[22:25]
	v_mfma_f32_16x16x32_bf16 v[26:29], v[54:57], v[238:241], v[26:29]
	v_mfma_f32_16x16x32_bf16 v[30:33], v[58:61], v[238:241], v[30:33]
	v_mfma_f32_16x16x32_bf16 v[34:37], v[62:65], v[238:241], v[34:37]
	v_mfma_f32_16x16x32_bf16 v[38:41], v[66:69], v[238:241], v[38:41]
	v_mfma_f32_16x16x32_bf16 v[6:9], v[70:73], v[238:241], v[6:9]
	ds_read_b128 v[238:241], v150 offset:1856
	ds_read_b128 v[70:73], v97 offset:5984
	s_waitcnt lgkmcnt(2)
	v_mfma_f32_16x16x32_bf16 v[14:17], v[74:77], v[10:13], v[14:17]
	v_mfma_f32_16x16x32_bf16 v[18:21], v[42:45], v[10:13], v[18:21]
	v_mfma_f32_16x16x32_bf16 v[22:25], v[46:49], v[10:13], v[22:25]
	v_mfma_f32_16x16x32_bf16 v[26:29], v[50:53], v[10:13], v[26:29]
	v_mfma_f32_16x16x32_bf16 v[30:33], v[54:57], v[10:13], v[30:33]
	v_mfma_f32_16x16x32_bf16 v[34:37], v[58:61], v[10:13], v[34:37]
	v_mfma_f32_16x16x32_bf16 v[38:41], v[62:65], v[10:13], v[38:41]
	v_mfma_f32_16x16x32_bf16 v[6:9], v[66:69], v[10:13], v[6:9]
	ds_read_b128 v[10:13], v150 offset:1920
	ds_read_b128 v[66:69], v97 offset:6048
	s_waitcnt lgkmcnt(2)
	v_mfma_f32_16x16x32_bf16 v[14:17], v[70:73], v[238:241], v[14:17]
	v_mfma_f32_16x16x32_bf16 v[18:21], v[74:77], v[238:241], v[18:21]
	v_mfma_f32_16x16x32_bf16 v[22:25], v[42:45], v[238:241], v[22:25]
	v_mfma_f32_16x16x32_bf16 v[26:29], v[46:49], v[238:241], v[26:29]
	v_mfma_f32_16x16x32_bf16 v[30:33], v[50:53], v[238:241], v[30:33]
	v_mfma_f32_16x16x32_bf16 v[34:37], v[54:57], v[238:241], v[34:37]
	v_mfma_f32_16x16x32_bf16 v[38:41], v[58:61], v[238:241], v[38:41]
	v_mfma_f32_16x16x32_bf16 v[6:9], v[62:65], v[238:241], v[6:9]
	ds_read_b128 v[238:241], v150 offset:1984
	ds_read_b128 v[62:65], v97 offset:6112
	s_waitcnt lgkmcnt(2)
	v_mfma_f32_16x16x32_bf16 v[14:17], v[66:69], v[10:13], v[14:17]
	v_mfma_f32_16x16x32_bf16 v[18:21], v[70:73], v[10:13], v[18:21]
	v_mfma_f32_16x16x32_bf16 v[22:25], v[74:77], v[10:13], v[22:25]
	v_mfma_f32_16x16x32_bf16 v[26:29], v[42:45], v[10:13], v[26:29]
	v_mfma_f32_16x16x32_bf16 v[30:33], v[46:49], v[10:13], v[30:33]
	v_mfma_f32_16x16x32_bf16 v[34:37], v[50:53], v[10:13], v[34:37]
	v_mfma_f32_16x16x32_bf16 v[38:41], v[54:57], v[10:13], v[38:41]
	v_mfma_f32_16x16x32_bf16 v[6:9], v[58:61], v[10:13], v[6:9]
	ds_read_b128 v[10:13], v150 offset:2048
	ds_read_b128 v[58:61], v97 offset:6176
	s_waitcnt lgkmcnt(2)
	v_mfma_f32_16x16x32_bf16 v[14:17], v[62:65], v[238:241], v[14:17]
	v_mfma_f32_16x16x32_bf16 v[18:21], v[66:69], v[238:241], v[18:21]
	v_mfma_f32_16x16x32_bf16 v[22:25], v[70:73], v[238:241], v[22:25]
	v_mfma_f32_16x16x32_bf16 v[26:29], v[74:77], v[238:241], v[26:29]
	v_mfma_f32_16x16x32_bf16 v[30:33], v[42:45], v[238:241], v[30:33]
	v_mfma_f32_16x16x32_bf16 v[34:37], v[46:49], v[238:241], v[34:37]
	v_mfma_f32_16x16x32_bf16 v[38:41], v[50:53], v[238:241], v[38:41]
	v_mfma_f32_16x16x32_bf16 v[6:9], v[54:57], v[238:241], v[6:9]
	ds_read_b128 v[238:241], v150 offset:2112
	ds_read_b128 v[54:57], v97 offset:6240
	s_waitcnt lgkmcnt(2)
	v_mfma_f32_16x16x32_bf16 v[14:17], v[58:61], v[10:13], v[14:17]
	v_mfma_f32_16x16x32_bf16 v[18:21], v[62:65], v[10:13], v[18:21]
	v_mfma_f32_16x16x32_bf16 v[22:25], v[66:69], v[10:13], v[22:25]
	v_mfma_f32_16x16x32_bf16 v[26:29], v[70:73], v[10:13], v[26:29]
	v_mfma_f32_16x16x32_bf16 v[30:33], v[74:77], v[10:13], v[30:33]
	v_mfma_f32_16x16x32_bf16 v[34:37], v[42:45], v[10:13], v[34:37]
	v_mfma_f32_16x16x32_bf16 v[38:41], v[46:49], v[10:13], v[38:41]
	v_mfma_f32_16x16x32_bf16 v[6:9], v[50:53], v[10:13], v[6:9]
	ds_read_b128 v[10:13], v150 offset:2176
	ds_read_b128 v[50:53], v97 offset:6304
	s_waitcnt lgkmcnt(2)
	v_mfma_f32_16x16x32_bf16 v[14:17], v[54:57], v[238:241], v[14:17]
	v_mfma_f32_16x16x32_bf16 v[18:21], v[58:61], v[238:241], v[18:21]
	v_mfma_f32_16x16x32_bf16 v[22:25], v[62:65], v[238:241], v[22:25]
	v_mfma_f32_16x16x32_bf16 v[26:29], v[66:69], v[238:241], v[26:29]
	v_mfma_f32_16x16x32_bf16 v[30:33], v[70:73], v[238:241], v[30:33]
	v_mfma_f32_16x16x32_bf16 v[34:37], v[74:77], v[238:241], v[34:37]
	v_mfma_f32_16x16x32_bf16 v[38:41], v[42:45], v[238:241], v[38:41]
	v_mfma_f32_16x16x32_bf16 v[6:9], v[46:49], v[238:241], v[6:9]
	ds_read_b128 v[238:241], v150 offset:2240
	ds_read_b128 v[46:49], v97 offset:6368
	s_waitcnt lgkmcnt(2)
	v_mfma_f32_16x16x32_bf16 v[14:17], v[50:53], v[10:13], v[14:17]
	v_mfma_f32_16x16x32_bf16 v[18:21], v[54:57], v[10:13], v[18:21]
	v_mfma_f32_16x16x32_bf16 v[22:25], v[58:61], v[10:13], v[22:25]
	v_mfma_f32_16x16x32_bf16 v[26:29], v[62:65], v[10:13], v[26:29]
	v_mfma_f32_16x16x32_bf16 v[30:33], v[66:69], v[10:13], v[30:33]
	v_mfma_f32_16x16x32_bf16 v[34:37], v[70:73], v[10:13], v[34:37]
	v_mfma_f32_16x16x32_bf16 v[38:41], v[74:77], v[10:13], v[38:41]
	v_mfma_f32_16x16x32_bf16 v[6:9], v[42:45], v[10:13], v[6:9]
	ds_read_b128 v[10:13], v150 offset:2304
	ds_read_b128 v[42:45], v97 offset:6432
	s_waitcnt lgkmcnt(2)
	v_mfma_f32_16x16x32_bf16 v[14:17], v[46:49], v[238:241], v[14:17]
	v_mfma_f32_16x16x32_bf16 v[18:21], v[50:53], v[238:241], v[18:21]
	v_mfma_f32_16x16x32_bf16 v[22:25], v[54:57], v[238:241], v[22:25]
	v_mfma_f32_16x16x32_bf16 v[26:29], v[58:61], v[238:241], v[26:29]
	v_mfma_f32_16x16x32_bf16 v[30:33], v[62:65], v[238:241], v[30:33]
	v_mfma_f32_16x16x32_bf16 v[34:37], v[66:69], v[238:241], v[34:37]
	v_mfma_f32_16x16x32_bf16 v[38:41], v[70:73], v[238:241], v[38:41]
	v_mfma_f32_16x16x32_bf16 v[6:9], v[74:77], v[238:241], v[6:9]
	ds_read_b128 v[238:241], v150 offset:2368
	ds_read_b128 v[74:77], v97 offset:6496
	s_waitcnt lgkmcnt(2)
	v_mfma_f32_16x16x32_bf16 v[14:17], v[42:45], v[10:13], v[14:17]
	v_mfma_f32_16x16x32_bf16 v[18:21], v[46:49], v[10:13], v[18:21]
	v_mfma_f32_16x16x32_bf16 v[22:25], v[50:53], v[10:13], v[22:25]
	v_mfma_f32_16x16x32_bf16 v[26:29], v[54:57], v[10:13], v[26:29]
	v_mfma_f32_16x16x32_bf16 v[30:33], v[58:61], v[10:13], v[30:33]
	v_mfma_f32_16x16x32_bf16 v[34:37], v[62:65], v[10:13], v[34:37]
	v_mfma_f32_16x16x32_bf16 v[38:41], v[66:69], v[10:13], v[38:41]
	v_mfma_f32_16x16x32_bf16 v[6:9], v[70:73], v[10:13], v[6:9]
	ds_read_b128 v[10:13], v150 offset:2432
	ds_read_b128 v[70:73], v97 offset:6560
	s_waitcnt lgkmcnt(2)
	v_mfma_f32_16x16x32_bf16 v[14:17], v[74:77], v[238:241], v[14:17]
	v_mfma_f32_16x16x32_bf16 v[18:21], v[42:45], v[238:241], v[18:21]
	v_mfma_f32_16x16x32_bf16 v[22:25], v[46:49], v[238:241], v[22:25]
	v_mfma_f32_16x16x32_bf16 v[26:29], v[50:53], v[238:241], v[26:29]
	v_mfma_f32_16x16x32_bf16 v[30:33], v[54:57], v[238:241], v[30:33]
	v_mfma_f32_16x16x32_bf16 v[34:37], v[58:61], v[238:241], v[34:37]
	v_mfma_f32_16x16x32_bf16 v[38:41], v[62:65], v[238:241], v[38:41]
	v_mfma_f32_16x16x32_bf16 v[6:9], v[66:69], v[238:241], v[6:9]
	ds_read_b128 v[238:241], v150 offset:2496
	ds_read_b128 v[66:69], v97 offset:6624
	s_waitcnt lgkmcnt(2)
	v_mfma_f32_16x16x32_bf16 v[14:17], v[70:73], v[10:13], v[14:17]
	v_mfma_f32_16x16x32_bf16 v[18:21], v[74:77], v[10:13], v[18:21]
	v_mfma_f32_16x16x32_bf16 v[22:25], v[42:45], v[10:13], v[22:25]
	v_mfma_f32_16x16x32_bf16 v[26:29], v[46:49], v[10:13], v[26:29]
	v_mfma_f32_16x16x32_bf16 v[30:33], v[50:53], v[10:13], v[30:33]
	v_mfma_f32_16x16x32_bf16 v[34:37], v[54:57], v[10:13], v[34:37]
	v_mfma_f32_16x16x32_bf16 v[38:41], v[58:61], v[10:13], v[38:41]
	v_mfma_f32_16x16x32_bf16 v[6:9], v[62:65], v[10:13], v[6:9]
	ds_read_b128 v[10:13], v150 offset:2560
	ds_read_b128 v[62:65], v97 offset:6688
	s_waitcnt lgkmcnt(2)
	v_mfma_f32_16x16x32_bf16 v[14:17], v[66:69], v[238:241], v[14:17]
	v_mfma_f32_16x16x32_bf16 v[18:21], v[70:73], v[238:241], v[18:21]
	v_mfma_f32_16x16x32_bf16 v[22:25], v[74:77], v[238:241], v[22:25]
	v_mfma_f32_16x16x32_bf16 v[26:29], v[42:45], v[238:241], v[26:29]
	v_mfma_f32_16x16x32_bf16 v[30:33], v[46:49], v[238:241], v[30:33]
	v_mfma_f32_16x16x32_bf16 v[34:37], v[50:53], v[238:241], v[34:37]
	v_mfma_f32_16x16x32_bf16 v[38:41], v[54:57], v[238:241], v[38:41]
	v_mfma_f32_16x16x32_bf16 v[6:9], v[58:61], v[238:241], v[6:9]
	ds_read_b128 v[238:241], v150 offset:2624
	ds_read_b128 v[58:61], v97 offset:6752
	s_waitcnt lgkmcnt(2)
	v_mfma_f32_16x16x32_bf16 v[14:17], v[62:65], v[10:13], v[14:17]
	v_mfma_f32_16x16x32_bf16 v[18:21], v[66:69], v[10:13], v[18:21]
	v_mfma_f32_16x16x32_bf16 v[22:25], v[70:73], v[10:13], v[22:25]
	v_mfma_f32_16x16x32_bf16 v[26:29], v[74:77], v[10:13], v[26:29]
	v_mfma_f32_16x16x32_bf16 v[30:33], v[42:45], v[10:13], v[30:33]
	v_mfma_f32_16x16x32_bf16 v[34:37], v[46:49], v[10:13], v[34:37]
	v_mfma_f32_16x16x32_bf16 v[38:41], v[50:53], v[10:13], v[38:41]
	v_mfma_f32_16x16x32_bf16 v[6:9], v[54:57], v[10:13], v[6:9]
	ds_read_b128 v[10:13], v150 offset:2688
	ds_read_b128 v[54:57], v97 offset:6816
	s_waitcnt lgkmcnt(2)
	v_mfma_f32_16x16x32_bf16 v[14:17], v[58:61], v[238:241], v[14:17]
	v_mfma_f32_16x16x32_bf16 v[18:21], v[62:65], v[238:241], v[18:21]
	v_mfma_f32_16x16x32_bf16 v[22:25], v[66:69], v[238:241], v[22:25]
	v_mfma_f32_16x16x32_bf16 v[26:29], v[70:73], v[238:241], v[26:29]
	v_mfma_f32_16x16x32_bf16 v[30:33], v[74:77], v[238:241], v[30:33]
	v_mfma_f32_16x16x32_bf16 v[34:37], v[42:45], v[238:241], v[34:37]
	v_mfma_f32_16x16x32_bf16 v[38:41], v[46:49], v[238:241], v[38:41]
	v_mfma_f32_16x16x32_bf16 v[6:9], v[50:53], v[238:241], v[6:9]
	ds_read_b128 v[238:241], v150 offset:2752
	ds_read_b128 v[50:53], v97 offset:6880
	s_waitcnt lgkmcnt(2)
	v_mfma_f32_16x16x32_bf16 v[14:17], v[54:57], v[10:13], v[14:17]
	v_mfma_f32_16x16x32_bf16 v[18:21], v[58:61], v[10:13], v[18:21]
	v_mfma_f32_16x16x32_bf16 v[22:25], v[62:65], v[10:13], v[22:25]
	v_mfma_f32_16x16x32_bf16 v[26:29], v[66:69], v[10:13], v[26:29]
	v_mfma_f32_16x16x32_bf16 v[30:33], v[70:73], v[10:13], v[30:33]
	v_mfma_f32_16x16x32_bf16 v[34:37], v[74:77], v[10:13], v[34:37]
	v_mfma_f32_16x16x32_bf16 v[38:41], v[42:45], v[10:13], v[38:41]
	v_mfma_f32_16x16x32_bf16 v[6:9], v[46:49], v[10:13], v[6:9]
	ds_read_b128 v[10:13], v150 offset:2816
	ds_read_b128 v[46:49], v97 offset:6944
	s_waitcnt lgkmcnt(2)
	v_mfma_f32_16x16x32_bf16 v[14:17], v[50:53], v[238:241], v[14:17]
	v_mfma_f32_16x16x32_bf16 v[18:21], v[54:57], v[238:241], v[18:21]
	v_mfma_f32_16x16x32_bf16 v[22:25], v[58:61], v[238:241], v[22:25]
	v_mfma_f32_16x16x32_bf16 v[26:29], v[62:65], v[238:241], v[26:29]
	v_mfma_f32_16x16x32_bf16 v[30:33], v[66:69], v[238:241], v[30:33]
	v_mfma_f32_16x16x32_bf16 v[34:37], v[70:73], v[238:241], v[34:37]
	v_mfma_f32_16x16x32_bf16 v[38:41], v[74:77], v[238:241], v[38:41]
	v_mfma_f32_16x16x32_bf16 v[6:9], v[42:45], v[238:241], v[6:9]
	ds_read_b128 v[238:241], v150 offset:2880
	ds_read_b128 v[42:45], v97 offset:7008
	s_waitcnt lgkmcnt(2)
	v_mfma_f32_16x16x32_bf16 v[14:17], v[46:49], v[10:13], v[14:17]
	v_mfma_f32_16x16x32_bf16 v[18:21], v[50:53], v[10:13], v[18:21]
	v_mfma_f32_16x16x32_bf16 v[22:25], v[54:57], v[10:13], v[22:25]
	v_mfma_f32_16x16x32_bf16 v[26:29], v[58:61], v[10:13], v[26:29]
	v_mfma_f32_16x16x32_bf16 v[30:33], v[62:65], v[10:13], v[30:33]
	v_mfma_f32_16x16x32_bf16 v[34:37], v[66:69], v[10:13], v[34:37]
	v_mfma_f32_16x16x32_bf16 v[38:41], v[70:73], v[10:13], v[38:41]
	v_mfma_f32_16x16x32_bf16 v[6:9], v[74:77], v[10:13], v[6:9]
	ds_read_b128 v[10:13], v150 offset:2944
	ds_read_b128 v[74:77], v97 offset:7072
	s_waitcnt lgkmcnt(2)
	v_mfma_f32_16x16x32_bf16 v[14:17], v[42:45], v[238:241], v[14:17]
	v_mfma_f32_16x16x32_bf16 v[18:21], v[46:49], v[238:241], v[18:21]
	v_mfma_f32_16x16x32_bf16 v[22:25], v[50:53], v[238:241], v[22:25]
	v_mfma_f32_16x16x32_bf16 v[26:29], v[54:57], v[238:241], v[26:29]
	v_mfma_f32_16x16x32_bf16 v[30:33], v[58:61], v[238:241], v[30:33]
	v_mfma_f32_16x16x32_bf16 v[34:37], v[62:65], v[238:241], v[34:37]
	v_mfma_f32_16x16x32_bf16 v[38:41], v[66:69], v[238:241], v[38:41]
	v_mfma_f32_16x16x32_bf16 v[6:9], v[70:73], v[238:241], v[6:9]
	ds_read_b128 v[238:241], v150 offset:3008
	ds_read_b128 v[70:73], v97 offset:7136
	s_waitcnt lgkmcnt(2)
	v_mfma_f32_16x16x32_bf16 v[14:17], v[74:77], v[10:13], v[14:17]
	v_mfma_f32_16x16x32_bf16 v[18:21], v[42:45], v[10:13], v[18:21]
	v_mfma_f32_16x16x32_bf16 v[22:25], v[46:49], v[10:13], v[22:25]
	v_mfma_f32_16x16x32_bf16 v[26:29], v[50:53], v[10:13], v[26:29]
	v_mfma_f32_16x16x32_bf16 v[30:33], v[54:57], v[10:13], v[30:33]
	v_mfma_f32_16x16x32_bf16 v[34:37], v[58:61], v[10:13], v[34:37]
	v_mfma_f32_16x16x32_bf16 v[38:41], v[62:65], v[10:13], v[38:41]
	v_mfma_f32_16x16x32_bf16 v[6:9], v[66:69], v[10:13], v[6:9]
	ds_read_b128 v[10:13], v150 offset:3072
	ds_read_b128 v[66:69], v97 offset:7200
	s_waitcnt lgkmcnt(2)
	v_mfma_f32_16x16x32_bf16 v[14:17], v[70:73], v[238:241], v[14:17]
	v_mfma_f32_16x16x32_bf16 v[18:21], v[74:77], v[238:241], v[18:21]
	v_mfma_f32_16x16x32_bf16 v[22:25], v[42:45], v[238:241], v[22:25]
	v_mfma_f32_16x16x32_bf16 v[26:29], v[46:49], v[238:241], v[26:29]
	v_mfma_f32_16x16x32_bf16 v[30:33], v[50:53], v[238:241], v[30:33]
	v_mfma_f32_16x16x32_bf16 v[34:37], v[54:57], v[238:241], v[34:37]
	v_mfma_f32_16x16x32_bf16 v[38:41], v[58:61], v[238:241], v[38:41]
	v_mfma_f32_16x16x32_bf16 v[6:9], v[62:65], v[238:241], v[6:9]
	ds_read_b128 v[238:241], v150 offset:3136
	ds_read_b128 v[62:65], v97 offset:7264
	s_waitcnt lgkmcnt(2)
	v_mfma_f32_16x16x32_bf16 v[14:17], v[66:69], v[10:13], v[14:17]
	v_mfma_f32_16x16x32_bf16 v[18:21], v[70:73], v[10:13], v[18:21]
	v_mfma_f32_16x16x32_bf16 v[22:25], v[74:77], v[10:13], v[22:25]
	v_mfma_f32_16x16x32_bf16 v[26:29], v[42:45], v[10:13], v[26:29]
	v_mfma_f32_16x16x32_bf16 v[30:33], v[46:49], v[10:13], v[30:33]
	v_mfma_f32_16x16x32_bf16 v[34:37], v[50:53], v[10:13], v[34:37]
	v_mfma_f32_16x16x32_bf16 v[38:41], v[54:57], v[10:13], v[38:41]
	v_mfma_f32_16x16x32_bf16 v[6:9], v[58:61], v[10:13], v[6:9]
	ds_read_b128 v[10:13], v150 offset:3200
	ds_read_b128 v[58:61], v97 offset:7328
	s_waitcnt lgkmcnt(2)
	v_mfma_f32_16x16x32_bf16 v[14:17], v[62:65], v[238:241], v[14:17]
	v_mfma_f32_16x16x32_bf16 v[18:21], v[66:69], v[238:241], v[18:21]
	v_mfma_f32_16x16x32_bf16 v[22:25], v[70:73], v[238:241], v[22:25]
	v_mfma_f32_16x16x32_bf16 v[26:29], v[74:77], v[238:241], v[26:29]
	v_mfma_f32_16x16x32_bf16 v[30:33], v[42:45], v[238:241], v[30:33]
	v_mfma_f32_16x16x32_bf16 v[34:37], v[46:49], v[238:241], v[34:37]
	v_mfma_f32_16x16x32_bf16 v[38:41], v[50:53], v[238:241], v[38:41]
	v_mfma_f32_16x16x32_bf16 v[6:9], v[54:57], v[238:241], v[6:9]
	ds_read_b128 v[238:241], v150 offset:3264
	ds_read_b128 v[54:57], v97 offset:7392
	s_waitcnt lgkmcnt(2)
	v_mfma_f32_16x16x32_bf16 v[14:17], v[58:61], v[10:13], v[14:17]
	v_mfma_f32_16x16x32_bf16 v[18:21], v[62:65], v[10:13], v[18:21]
	v_mfma_f32_16x16x32_bf16 v[22:25], v[66:69], v[10:13], v[22:25]
	v_mfma_f32_16x16x32_bf16 v[26:29], v[70:73], v[10:13], v[26:29]
	v_mfma_f32_16x16x32_bf16 v[30:33], v[74:77], v[10:13], v[30:33]
	v_mfma_f32_16x16x32_bf16 v[34:37], v[42:45], v[10:13], v[34:37]
	v_mfma_f32_16x16x32_bf16 v[38:41], v[46:49], v[10:13], v[38:41]
	v_mfma_f32_16x16x32_bf16 v[6:9], v[50:53], v[10:13], v[6:9]
	ds_read_b128 v[10:13], v150 offset:3328
	ds_read_b128 v[50:53], v97 offset:7456
	s_waitcnt lgkmcnt(2)
	v_mfma_f32_16x16x32_bf16 v[14:17], v[54:57], v[238:241], v[14:17]
	v_mfma_f32_16x16x32_bf16 v[18:21], v[58:61], v[238:241], v[18:21]
	v_mfma_f32_16x16x32_bf16 v[22:25], v[62:65], v[238:241], v[22:25]
	v_mfma_f32_16x16x32_bf16 v[26:29], v[66:69], v[238:241], v[26:29]
	v_mfma_f32_16x16x32_bf16 v[30:33], v[70:73], v[238:241], v[30:33]
	v_mfma_f32_16x16x32_bf16 v[34:37], v[74:77], v[238:241], v[34:37]
	v_mfma_f32_16x16x32_bf16 v[38:41], v[42:45], v[238:241], v[38:41]
	v_mfma_f32_16x16x32_bf16 v[6:9], v[46:49], v[238:241], v[6:9]
	ds_read_b128 v[238:241], v150 offset:3392
	ds_read_b128 v[46:49], v97 offset:7520
	s_waitcnt lgkmcnt(2)
	v_mfma_f32_16x16x32_bf16 v[14:17], v[50:53], v[10:13], v[14:17]
	v_mfma_f32_16x16x32_bf16 v[18:21], v[54:57], v[10:13], v[18:21]
	v_mfma_f32_16x16x32_bf16 v[22:25], v[58:61], v[10:13], v[22:25]
	v_mfma_f32_16x16x32_bf16 v[26:29], v[62:65], v[10:13], v[26:29]
	v_mfma_f32_16x16x32_bf16 v[30:33], v[66:69], v[10:13], v[30:33]
	v_mfma_f32_16x16x32_bf16 v[34:37], v[70:73], v[10:13], v[34:37]
	v_mfma_f32_16x16x32_bf16 v[38:41], v[74:77], v[10:13], v[38:41]
	v_mfma_f32_16x16x32_bf16 v[6:9], v[42:45], v[10:13], v[6:9]
	ds_read_b128 v[10:13], v150 offset:3456
	ds_read_b128 v[42:45], v97 offset:7584
	s_waitcnt lgkmcnt(2)
	v_mfma_f32_16x16x32_bf16 v[14:17], v[46:49], v[238:241], v[14:17]
	v_mfma_f32_16x16x32_bf16 v[18:21], v[50:53], v[238:241], v[18:21]
	v_mfma_f32_16x16x32_bf16 v[22:25], v[54:57], v[238:241], v[22:25]
	v_mfma_f32_16x16x32_bf16 v[26:29], v[58:61], v[238:241], v[26:29]
	v_mfma_f32_16x16x32_bf16 v[30:33], v[62:65], v[238:241], v[30:33]
	v_mfma_f32_16x16x32_bf16 v[34:37], v[66:69], v[238:241], v[34:37]
	v_mfma_f32_16x16x32_bf16 v[38:41], v[70:73], v[238:241], v[38:41]
	v_mfma_f32_16x16x32_bf16 v[6:9], v[74:77], v[238:241], v[6:9]
	ds_read_b128 v[238:241], v150 offset:3520
	ds_read_b128 v[74:77], v97 offset:7648
	s_waitcnt lgkmcnt(2)
	v_mfma_f32_16x16x32_bf16 v[14:17], v[42:45], v[10:13], v[14:17]
	v_mfma_f32_16x16x32_bf16 v[18:21], v[46:49], v[10:13], v[18:21]
	v_mfma_f32_16x16x32_bf16 v[22:25], v[50:53], v[10:13], v[22:25]
	v_mfma_f32_16x16x32_bf16 v[26:29], v[54:57], v[10:13], v[26:29]
	v_mfma_f32_16x16x32_bf16 v[30:33], v[58:61], v[10:13], v[30:33]
	v_mfma_f32_16x16x32_bf16 v[34:37], v[62:65], v[10:13], v[34:37]
	v_mfma_f32_16x16x32_bf16 v[38:41], v[66:69], v[10:13], v[38:41]
	v_mfma_f32_16x16x32_bf16 v[6:9], v[70:73], v[10:13], v[6:9]
	ds_read_b128 v[10:13], v150 offset:3584
	ds_read_b128 v[70:73], v97 offset:7712
	s_waitcnt lgkmcnt(2)
	v_mfma_f32_16x16x32_bf16 v[14:17], v[74:77], v[238:241], v[14:17]
	v_mfma_f32_16x16x32_bf16 v[18:21], v[42:45], v[238:241], v[18:21]
	v_mfma_f32_16x16x32_bf16 v[22:25], v[46:49], v[238:241], v[22:25]
	v_mfma_f32_16x16x32_bf16 v[26:29], v[50:53], v[238:241], v[26:29]
	v_mfma_f32_16x16x32_bf16 v[30:33], v[54:57], v[238:241], v[30:33]
	v_mfma_f32_16x16x32_bf16 v[34:37], v[58:61], v[238:241], v[34:37]
	v_mfma_f32_16x16x32_bf16 v[38:41], v[62:65], v[238:241], v[38:41]
	v_mfma_f32_16x16x32_bf16 v[6:9], v[66:69], v[238:241], v[6:9]
	ds_read_b128 v[66:69], v97 offset:7776
	s_waitcnt lgkmcnt(1)
	v_mfma_f32_16x16x32_bf16 v[14:17], v[70:73], v[10:13], v[14:17]
	v_mfma_f32_16x16x32_bf16 v[18:21], v[74:77], v[10:13], v[18:21]
	v_mfma_f32_16x16x32_bf16 v[22:25], v[42:45], v[10:13], v[22:25]
	v_mfma_f32_16x16x32_bf16 v[26:29], v[46:49], v[10:13], v[26:29]
	v_mfma_f32_16x16x32_bf16 v[30:33], v[50:53], v[10:13], v[30:33]
	v_mfma_f32_16x16x32_bf16 v[34:37], v[54:57], v[10:13], v[34:37]
	v_mfma_f32_16x16x32_bf16 v[38:41], v[58:61], v[10:13], v[38:41]
	v_mfma_f32_16x16x32_bf16 v[6:9], v[62:65], v[10:13], v[6:9]
	ds_read_b128 v[10:13], v150 offset:3648
	ds_read_b128 v[62:65], v97 offset:7840
	s_waitcnt lgkmcnt(1)
	v_mfma_f32_16x16x32_bf16 v[14:17], v[66:69], v[10:13], v[14:17]
	v_mfma_f32_16x16x32_bf16 v[18:21], v[70:73], v[10:13], v[18:21]
	v_mfma_f32_16x16x32_bf16 v[22:25], v[74:77], v[10:13], v[22:25]
	v_mfma_f32_16x16x32_bf16 v[26:29], v[42:45], v[10:13], v[26:29]
	v_mfma_f32_16x16x32_bf16 v[30:33], v[46:49], v[10:13], v[30:33]
	v_mfma_f32_16x16x32_bf16 v[34:37], v[50:53], v[10:13], v[34:37]
	v_mfma_f32_16x16x32_bf16 v[38:41], v[54:57], v[10:13], v[38:41]
	v_mfma_f32_16x16x32_bf16 v[10:13], v[58:61], v[10:13], v[6:9]
	ds_read_b128 v[58:61], v150 offset:3712
	s_nop 1
	ds_read_b128 v[6:9], v97 offset:7904
	s_waitcnt lgkmcnt(1)
	v_mfma_f32_16x16x32_bf16 v[14:17], v[62:65], v[58:61], v[14:17]
	v_mfma_f32_16x16x32_bf16 v[18:21], v[66:69], v[58:61], v[18:21]
	v_mfma_f32_16x16x32_bf16 v[22:25], v[70:73], v[58:61], v[22:25]
	v_mfma_f32_16x16x32_bf16 v[26:29], v[74:77], v[58:61], v[26:29]
	v_mfma_f32_16x16x32_bf16 v[30:33], v[42:45], v[58:61], v[30:33]
	v_mfma_f32_16x16x32_bf16 v[34:37], v[46:49], v[58:61], v[34:37]
	v_mfma_f32_16x16x32_bf16 v[38:41], v[50:53], v[58:61], v[38:41]
	v_mfma_f32_16x16x32_bf16 v[54:57], v[54:57], v[58:61], v[10:13]
	ds_read_b128 v[58:61], v150 offset:3776
	s_nop 1
	ds_read_b128 v[10:13], v97 offset:7968
	s_waitcnt lgkmcnt(1)
	v_mfma_f32_16x16x32_bf16 v[50:53], v[50:53], v[58:61], v[54:57]
	s_nop 2
	ds_read_b128 v[54:57], v150 offset:3840
	v_mfma_f32_16x16x32_bf16 v[14:17], v[6:9], v[58:61], v[14:17]
	v_mfma_f32_16x16x32_bf16 v[18:21], v[62:65], v[58:61], v[18:21]
	v_mfma_f32_16x16x32_bf16 v[22:25], v[66:69], v[58:61], v[22:25]
	v_mfma_f32_16x16x32_bf16 v[26:29], v[70:73], v[58:61], v[26:29]
	v_mfma_f32_16x16x32_bf16 v[30:33], v[74:77], v[58:61], v[30:33]
	v_mfma_f32_16x16x32_bf16 v[34:37], v[42:45], v[58:61], v[34:37]
	v_mfma_f32_16x16x32_bf16 v[38:41], v[46:49], v[58:61], v[38:41]
	s_waitcnt lgkmcnt(0)
	v_mfma_f32_16x16x32_bf16 v[58:61], v[10:13], v[54:57], v[14:17]
	s_nop 2
	ds_read_b128 v[14:17], v97 offset:8032
	v_mfma_f32_16x16x32_bf16 v[46:49], v[46:49], v[54:57], v[50:53]
	s_nop 2
	ds_read_b128 v[50:53], v150 offset:3904
	v_mfma_f32_16x16x32_bf16 v[18:21], v[6:9], v[54:57], v[18:21]
	v_mfma_f32_16x16x32_bf16 v[22:25], v[62:65], v[54:57], v[22:25]
	v_mfma_f32_16x16x32_bf16 v[26:29], v[66:69], v[54:57], v[26:29]
	v_mfma_f32_16x16x32_bf16 v[30:33], v[70:73], v[54:57], v[30:33]
	v_mfma_f32_16x16x32_bf16 v[34:37], v[74:77], v[54:57], v[34:37]
	v_mfma_f32_16x16x32_bf16 v[38:41], v[42:45], v[54:57], v[38:41]
	s_waitcnt lgkmcnt(0)
	v_mfma_f32_16x16x32_bf16 v[54:57], v[14:17], v[50:53], v[58:61]
	v_mfma_f32_16x16x32_bf16 v[58:61], v[10:13], v[50:53], v[18:21]
	s_nop 2
	ds_read_b128 v[18:21], v97 offset:8096
	v_mfma_f32_16x16x32_bf16 v[42:45], v[42:45], v[50:53], v[46:49]
	s_nop 2
	ds_read_b128 v[46:49], v150 offset:3968
	v_mfma_f32_16x16x32_bf16 v[22:25], v[6:9], v[50:53], v[22:25]
	v_mfma_f32_16x16x32_bf16 v[26:29], v[62:65], v[50:53], v[26:29]
	v_mfma_f32_16x16x32_bf16 v[30:33], v[66:69], v[50:53], v[30:33]
	v_mfma_f32_16x16x32_bf16 v[34:37], v[70:73], v[50:53], v[34:37]
	v_mfma_f32_16x16x32_bf16 v[38:41], v[74:77], v[50:53], v[38:41]
	s_waitcnt lgkmcnt(0)
	v_mfma_f32_16x16x32_bf16 v[50:53], v[18:21], v[46:49], v[54:57]
	v_mfma_f32_16x16x32_bf16 v[54:57], v[14:17], v[46:49], v[58:61]
	v_mfma_f32_16x16x32_bf16 v[58:61], v[10:13], v[46:49], v[22:25]
	v_mfma_f32_16x16x32_bf16 v[26:29], v[6:9], v[46:49], v[26:29]
	s_nop 1
	ds_read_b128 v[22:25], v97 offset:8160
	v_mfma_f32_16x16x32_bf16 v[30:33], v[62:65], v[46:49], v[30:33]
	v_mfma_f32_16x16x32_bf16 v[34:37], v[66:69], v[46:49], v[34:37]
	v_mfma_f32_16x16x32_bf16 v[38:41], v[70:73], v[46:49], v[38:41]
	v_mfma_f32_16x16x32_bf16 v[42:45], v[74:77], v[46:49], v[42:45]
	ds_read_b128 v[46:49], v150 offset:4032
	s_waitcnt lgkmcnt(0)
	v_mfma_f32_16x16x32_bf16 v[74:77], v[6:9], v[46:49], v[30:33]
	s_nop 2
	ds_read_b128 v[30:33], v97 offset:8224
	v_mfma_f32_16x16x32_bf16 v[42:45], v[70:73], v[46:49], v[42:45]
	ds_read_b128 v[70:73], v150 offset:4096
	v_mfma_f32_16x16x32_bf16 v[50:53], v[22:25], v[46:49], v[50:53]
	v_mfma_f32_16x16x32_bf16 v[54:57], v[18:21], v[46:49], v[54:57]
	v_mfma_f32_16x16x32_bf16 v[58:61], v[14:17], v[46:49], v[58:61]
	v_mfma_f32_16x16x32_bf16 v[26:29], v[10:13], v[46:49], v[26:29]
	v_mfma_f32_16x16x32_bf16 v[34:37], v[62:65], v[46:49], v[34:37]
	v_mfma_f32_16x16x32_bf16 v[38:41], v[66:69], v[46:49], v[38:41]
	ds_read_b128 v[46:49], v97 offset:8288
	s_waitcnt lgkmcnt(1)
	v_mfma_f32_16x16x32_bf16 v[50:53], v[30:33], v[70:73], v[50:53]
	v_mfma_f32_16x16x32_bf16 v[54:57], v[22:25], v[70:73], v[54:57]
	v_mfma_f32_16x16x32_bf16 v[80:83], v[18:21], v[70:73], v[58:61]
	v_mfma_f32_16x16x32_bf16 v[26:29], v[14:17], v[70:73], v[26:29]
	v_mfma_f32_16x16x32_bf16 v[74:77], v[10:13], v[70:73], v[74:77]
	v_mfma_f32_16x16x32_bf16 v[34:37], v[6:9], v[70:73], v[34:37]
	v_mfma_f32_16x16x32_bf16 v[132:135], v[62:65], v[70:73], v[38:41]
	v_mfma_f32_16x16x32_bf16 v[66:69], v[66:69], v[70:73], v[42:45]
	ds_read_b128 v[70:73], v150 offset:4160
	s_waitcnt lgkmcnt(0)
	v_mfma_f32_16x16x32_bf16 v[62:65], v[62:65], v[70:73], v[66:69]
	s_nop 4
	ds_read_b128 v[66:69], v150 offset:4224
	v_mfma_f32_16x16x32_bf16 v[42:45], v[18:21], v[70:73], v[26:29]
	v_mfma_f32_16x16x32_bf16 v[38:41], v[14:17], v[70:73], v[74:77]
	v_mfma_f32_16x16x32_bf16 v[26:29], v[6:9], v[70:73], v[132:135]
	s_nop 1
	ds_read_b128 v[74:77], v97 offset:8352
	s_waitcnt lgkmcnt(0)
	s_barrier
	v_lshlrev_b32_e32 v134, 1, v96
	v_mov_b32_e32 v135, v131
	v_mfma_f32_16x16x32_bf16 v[58:61], v[46:49], v[70:73], v[50:53]
	v_mfma_f32_16x16x32_bf16 v[50:53], v[22:25], v[70:73], v[80:83]
	v_mfma_f32_16x16x32_bf16 v[22:25], v[22:25], v[66:69], v[42:45]
	s_nop 2
	v_lshl_add_u64 v[42:43], s[2:3], 0, v[134:135]
	v_mfma_f32_16x16x32_bf16 v[18:21], v[18:21], v[66:69], v[38:41]
	s_nop 2
	v_lshl_add_u64 v[38:39], v[98:99], 1, v[42:43]
	v_add_co_u32_e32 v40, vcc, 0x4000, v38
	v_mfma_f32_16x16x32_bf16 v[54:57], v[30:33], v[70:73], v[54:57]
	s_nop 0
	v_addc_co_u32_e32 v41, vcc, 0, v39, vcc
	global_load_dwordx2 v[84:85], v[40:41], off
	v_mfma_f32_16x16x32_bf16 v[34:37], v[10:13], v[70:73], v[34:37]
	v_lshl_add_u64 v[132:133], v[38:39], 0, s[16:17]
	v_mfma_f32_16x16x32_bf16 v[58:61], v[74:77], v[66:69], v[58:61]
	v_mov_b32_e32 v75, 0
	v_mfma_f32_16x16x32_bf16 v[46:49], v[46:49], v[66:69], v[54:57]
	v_mfma_f32_16x16x32_bf16 v[30:33], v[30:33], v[66:69], v[50:53]
	v_mfma_f32_16x16x32_bf16 v[14:17], v[14:17], v[66:69], v[34:37]
	v_mfma_f32_16x16x32_bf16 v[10:13], v[10:13], v[66:69], v[26:29]
	v_mfma_f32_16x16x32_bf16 v[6:9], v[6:9], v[66:69], v[62:65]
	s_mov_b64 s[0:1], exec
	v_readlane_b32 s4, v255, 37
	v_readlane_b32 s5, v255, 38
	s_and_b64 s[4:5], s[0:1], s[4:5]
	s_mov_b64 exec, s[4:5]
	s_cbranch_execz .LBB0_802
	global_load_short_d16_hi v137, v[132:133], off offset:-2

.LBB0_866:
	s_or_b64 exec, exec, s[4:5]
	ds_read_b128 v[14:17], v97 offset:4064
	ds_read_b128 v[18:21], v97 offset:4000
	ds_read_b128 v[46:49], v149
	ds_read_b128 v[42:45], v97 offset:3680
	ds_read_b128 v[74:77], v97 offset:3616
	ds_read_b128 v[26:29], v97 offset:3936
	ds_read_b128 v[30:33], v97 offset:3872
	ds_read_b128 v[34:37], v97 offset:3808
	ds_read_b128 v[38:41], v97 offset:3744
	ds_read_b128 v[22:25], v97 offset:4128
	ds_read_b128 v[78:81], v150
	s_waitcnt lgkmcnt(7)
	v_mfma_f32_16x16x32_bf16 v[82:85], v[42:45], v[46:49], 0
	s_add_i32 s4, s24, 0x1000
	s_mul_hi_i32 s5, s4, 0xc000
	s_mul_i32 s4, s4, 0xc000
	v_mfma_f32_16x16x32_bf16 v[50:53], v[14:17], v[46:49], 0
	s_add_u32 s42, s20, s4
	s_addc_u32 s43, s68, s5
	v_mov_b32_e32 v135, v131
	v_mfma_f32_16x16x32_bf16 v[54:57], v[18:21], v[46:49], 0
	s_waitcnt lgkmcnt(5)
	v_mfma_f32_16x16x32_bf16 v[58:61], v[26:29], v[46:49], 0
	s_waitcnt lgkmcnt(4)
	v_mfma_f32_16x16x32_bf16 v[62:65], v[30:33], v[46:49], 0
	s_waitcnt lgkmcnt(3)
	v_mfma_f32_16x16x32_bf16 v[66:69], v[34:37], v[46:49], 0
	s_waitcnt lgkmcnt(2)
	v_mfma_f32_16x16x32_bf16 v[70:73], v[38:41], v[46:49], 0
	v_mfma_f32_16x16x32_bf16 v[46:49], v[74:77], v[46:49], 0
	s_waitcnt lgkmcnt(0)
	v_mfma_f32_16x16x32_bf16 v[74:77], v[38:41], v[78:81], v[82:85]
	s_nop 2
	ds_read_b128 v[82:85], v97 offset:4192
	v_mfma_f32_16x16x32_bf16 v[42:45], v[42:45], v[78:81], v[46:49]
	s_nop 2
	ds_read_b128 v[46:49], v150 offset:64
	v_mfma_f32_16x16x32_bf16 v[50:53], v[22:25], v[78:81], v[50:53]
	v_mfma_f32_16x16x32_bf16 v[54:57], v[14:17], v[78:81], v[54:57]
	v_mfma_f32_16x16x32_bf16 v[58:61], v[18:21], v[78:81], v[58:61]
	v_mfma_f32_16x16x32_bf16 v[62:65], v[26:29], v[78:81], v[62:65]
	v_mfma_f32_16x16x32_bf16 v[66:69], v[30:33], v[78:81], v[66:69]
	v_mfma_f32_16x16x32_bf16 v[70:73], v[34:37], v[78:81], v[70:73]
	ds_read_b128 v[78:81], v97 offset:4256
	s_waitcnt lgkmcnt(1)
	v_mfma_f32_16x16x32_bf16 v[38:41], v[38:41], v[46:49], v[42:45]
	s_nop 2
	ds_read_b128 v[42:45], v150 offset:128
	v_mfma_f32_16x16x32_bf16 v[50:53], v[82:85], v[46:49], v[50:53]
	v_mfma_f32_16x16x32_bf16 v[54:57], v[22:25], v[46:49], v[54:57]
	v_mfma_f32_16x16x32_bf16 v[58:61], v[14:17], v[46:49], v[58:61]
	v_mfma_f32_16x16x32_bf16 v[62:65], v[18:21], v[46:49], v[62:65]
	v_mfma_f32_16x16x32_bf16 v[66:69], v[26:29], v[46:49], v[66:69]
	v_mfma_f32_16x16x32_bf16 v[70:73], v[30:33], v[46:49], v[70:73]
	v_mfma_f32_16x16x32_bf16 v[74:77], v[34:37], v[46:49], v[74:77]
	s_waitcnt lgkmcnt(0)
	v_mfma_f32_16x16x32_bf16 v[46:49], v[78:81], v[42:45], v[50:53]
	v_mfma_f32_16x16x32_bf16 v[50:53], v[82:85], v[42:45], v[54:57]
	v_mfma_f32_16x16x32_bf16 v[54:57], v[22:25], v[42:45], v[58:61]
	v_mfma_f32_16x16x32_bf16 v[58:61], v[14:17], v[42:45], v[62:65]
	v_mfma_f32_16x16x32_bf16 v[62:65], v[18:21], v[42:45], v[66:69]
	v_mfma_f32_16x16x32_bf16 v[66:69], v[26:29], v[42:45], v[70:73]
	v_mfma_f32_16x16x32_bf16 v[70:73], v[30:33], v[42:45], v[74:77]
	s_nop 2
	ds_read_b128 v[74:77], v97 offset:4320
	v_mfma_f32_16x16x32_bf16 v[34:37], v[34:37], v[42:45], v[38:41]
	s_nop 2
	ds_read_b128 v[38:41], v150 offset:192
	s_waitcnt lgkmcnt(0)
	v_mfma_f32_16x16x32_bf16 v[42:45], v[74:77], v[38:41], v[46:49]
	v_mfma_f32_16x16x32_bf16 v[46:49], v[78:81], v[38:41], v[50:53]
	v_mfma_f32_16x16x32_bf16 v[50:53], v[82:85], v[38:41], v[54:57]
	v_mfma_f32_16x16x32_bf16 v[54:57], v[22:25], v[38:41], v[58:61]
	v_mfma_f32_16x16x32_bf16 v[58:61], v[14:17], v[38:41], v[62:65]
	v_mfma_f32_16x16x32_bf16 v[62:65], v[18:21], v[38:41], v[66:69]
	v_mfma_f32_16x16x32_bf16 v[66:69], v[26:29], v[38:41], v[70:73]
	s_nop 2
	ds_read_b128 v[70:73], v97 offset:4384
	v_mfma_f32_16x16x32_bf16 v[30:33], v[30:33], v[38:41], v[34:37]
	s_nop 2
	ds_read_b128 v[34:37], v150 offset:256
	s_waitcnt lgkmcnt(0)
	v_mfma_f32_16x16x32_bf16 v[38:41], v[70:73], v[34:37], v[42:45]
	v_mfma_f32_16x16x32_bf16 v[42:45], v[74:77], v[34:37], v[46:49]
	v_mfma_f32_16x16x32_bf16 v[46:49], v[78:81], v[34:37], v[50:53]
	v_mfma_f32_16x16x32_bf16 v[50:53], v[82:85], v[34:37], v[54:57]
	v_mfma_f32_16x16x32_bf16 v[54:57], v[22:25], v[34:37], v[58:61]
	v_mfma_f32_16x16x32_bf16 v[58:61], v[14:17], v[34:37], v[62:65]
	v_mfma_f32_16x16x32_bf16 v[62:65], v[18:21], v[34:37], v[66:69]
	s_nop 2
	ds_read_b128 v[66:69], v97 offset:4448
	v_mfma_f32_16x16x32_bf16 v[26:29], v[26:29], v[34:37], v[30:33]
	s_nop 2
	ds_read_b128 v[30:33], v150 offset:320
	s_waitcnt lgkmcnt(0)
	v_mfma_f32_16x16x32_bf16 v[34:37], v[66:69], v[30:33], v[38:41]
	v_mfma_f32_16x16x32_bf16 v[38:41], v[70:73], v[30:33], v[42:45]
	v_mfma_f32_16x16x32_bf16 v[42:45], v[74:77], v[30:33], v[46:49]
	v_mfma_f32_16x16x32_bf16 v[46:49], v[78:81], v[30:33], v[50:53]
	v_mfma_f32_16x16x32_bf16 v[50:53], v[82:85], v[30:33], v[54:57]
	v_mfma_f32_16x16x32_bf16 v[54:57], v[22:25], v[30:33], v[58:61]
	v_mfma_f32_16x16x32_bf16 v[58:61], v[14:17], v[30:33], v[62:65]
	s_nop 2
	ds_read_b128 v[62:65], v97 offset:4512
	v_mfma_f32_16x16x32_bf16 v[18:21], v[18:21], v[30:33], v[26:29]
	s_nop 2
	ds_read_b128 v[26:29], v150 offset:384
	s_waitcnt lgkmcnt(0)
	v_mfma_f32_16x16x32_bf16 v[30:33], v[62:65], v[26:29], v[34:37]
	v_mfma_f32_16x16x32_bf16 v[34:37], v[66:69], v[26:29], v[38:41]
	v_mfma_f32_16x16x32_bf16 v[38:41], v[70:73], v[26:29], v[42:45]
	v_mfma_f32_16x16x32_bf16 v[42:45], v[74:77], v[26:29], v[46:49]
	v_mfma_f32_16x16x32_bf16 v[46:49], v[78:81], v[26:29], v[50:53]
	v_mfma_f32_16x16x32_bf16 v[50:53], v[82:85], v[26:29], v[54:57]
	v_mfma_f32_16x16x32_bf16 v[54:57], v[22:25], v[26:29], v[58:61]
	s_nop 2
	ds_read_b128 v[58:61], v97 offset:4576
	v_mfma_f32_16x16x32_bf16 v[14:17], v[14:17], v[26:29], v[18:21]
	s_nop 2
	ds_read_b128 v[18:21], v150 offset:448
	s_waitcnt lgkmcnt(0)
	v_mfma_f32_16x16x32_bf16 v[26:29], v[58:61], v[18:21], v[30:33]
	v_mfma_f32_16x16x32_bf16 v[30:33], v[62:65], v[18:21], v[34:37]
	v_mfma_f32_16x16x32_bf16 v[34:37], v[66:69], v[18:21], v[38:41]
	v_mfma_f32_16x16x32_bf16 v[38:41], v[70:73], v[18:21], v[42:45]
	v_mfma_f32_16x16x32_bf16 v[42:45], v[74:77], v[18:21], v[46:49]
	v_mfma_f32_16x16x32_bf16 v[46:49], v[78:81], v[18:21], v[50:53]
	v_mfma_f32_16x16x32_bf16 v[50:53], v[82:85], v[18:21], v[54:57]
	s_nop 2
	ds_read_b128 v[54:57], v97 offset:4640
	v_mfma_f32_16x16x32_bf16 v[14:17], v[22:25], v[18:21], v[14:17]
	ds_read_b128 v[18:21], v150 offset:512
	s_waitcnt lgkmcnt(0)
	v_mfma_f32_16x16x32_bf16 v[14:17], v[82:85], v[18:21], v[14:17]
	ds_read_b128 v[82:85], v97 offset:4768
	v_mfma_f32_16x16x32_bf16 v[22:25], v[54:57], v[18:21], v[26:29]
	v_mfma_f32_16x16x32_bf16 v[26:29], v[58:61], v[18:21], v[30:33]
	v_mfma_f32_16x16x32_bf16 v[30:33], v[62:65], v[18:21], v[34:37]
	v_mfma_f32_16x16x32_bf16 v[34:37], v[66:69], v[18:21], v[38:41]
	v_mfma_f32_16x16x32_bf16 v[38:41], v[70:73], v[18:21], v[42:45]
	v_mfma_f32_16x16x32_bf16 v[42:45], v[74:77], v[18:21], v[46:49]
	v_mfma_f32_16x16x32_bf16 v[46:49], v[78:81], v[18:21], v[50:53]
	ds_read_b128 v[18:21], v150 offset:576
	s_nop 1
	ds_read_b128 v[50:53], v97 offset:4704
	s_waitcnt lgkmcnt(1)
	v_mfma_f32_16x16x32_bf16 v[26:29], v[54:57], v[18:21], v[26:29]
	v_mfma_f32_16x16x32_bf16 v[30:33], v[58:61], v[18:21], v[30:33]
	v_mfma_f32_16x16x32_bf16 v[34:37], v[62:65], v[18:21], v[34:37]
	v_mfma_f32_16x16x32_bf16 v[38:41], v[66:69], v[18:21], v[38:41]
	v_mfma_f32_16x16x32_bf16 v[42:45], v[70:73], v[18:21], v[42:45]
	v_mfma_f32_16x16x32_bf16 v[46:49], v[74:77], v[18:21], v[46:49]
	v_mfma_f32_16x16x32_bf16 v[14:17], v[78:81], v[18:21], v[14:17]
	ds_read_b128 v[78:81], v97 offset:4832
	s_waitcnt lgkmcnt(1)
	v_mfma_f32_16x16x32_bf16 v[22:25], v[50:53], v[18:21], v[22:25]
	ds_read_b128 v[18:21], v150 offset:640
	s_waitcnt lgkmcnt(0)
	ds_read_b128 v[238:241], v150 offset:704
	v_mfma_f32_16x16x32_bf16 v[22:25], v[82:85], v[18:21], v[22:25]
	v_mfma_f32_16x16x32_bf16 v[26:29], v[50:53], v[18:21], v[26:29]
	v_mfma_f32_16x16x32_bf16 v[30:33], v[54:57], v[18:21], v[30:33]
	v_mfma_f32_16x16x32_bf16 v[34:37], v[58:61], v[18:21], v[34:37]
	v_mfma_f32_16x16x32_bf16 v[38:41], v[62:65], v[18:21], v[38:41]
	v_mfma_f32_16x16x32_bf16 v[42:45], v[66:69], v[18:21], v[42:45]
	v_mfma_f32_16x16x32_bf16 v[46:49], v[70:73], v[18:21], v[46:49]
	v_mfma_f32_16x16x32_bf16 v[14:17], v[74:77], v[18:21], v[14:17]
	ds_read_b128 v[18:21], v150 offset:768
	ds_read_b128 v[74:77], v97 offset:4896
	s_waitcnt lgkmcnt(2)
	v_mfma_f32_16x16x32_bf16 v[22:25], v[78:81], v[238:241], v[22:25]
	v_mfma_f32_16x16x32_bf16 v[26:29], v[82:85], v[238:241], v[26:29]
	v_mfma_f32_16x16x32_bf16 v[30:33], v[50:53], v[238:241], v[30:33]
	v_mfma_f32_16x16x32_bf16 v[34:37], v[54:57], v[238:241], v[34:37]
	v_mfma_f32_16x16x32_bf16 v[38:41], v[58:61], v[238:241], v[38:41]
	v_mfma_f32_16x16x32_bf16 v[42:45], v[62:65], v[238:241], v[42:45]
	v_mfma_f32_16x16x32_bf16 v[46:49], v[66:69], v[238:241], v[46:49]
	v_mfma_f32_16x16x32_bf16 v[14:17], v[70:73], v[238:241], v[14:17]
	ds_read_b128 v[238:241], v150 offset:832
	ds_read_b128 v[70:73], v97 offset:4960
	s_waitcnt lgkmcnt(2)
	v_mfma_f32_16x16x32_bf16 v[22:25], v[74:77], v[18:21], v[22:25]
	v_mfma_f32_16x16x32_bf16 v[26:29], v[78:81], v[18:21], v[26:29]
	v_mfma_f32_16x16x32_bf16 v[30:33], v[82:85], v[18:21], v[30:33]
	v_mfma_f32_16x16x32_bf16 v[34:37], v[50:53], v[18:21], v[34:37]
	v_mfma_f32_16x16x32_bf16 v[38:41], v[54:57], v[18:21], v[38:41]
	v_mfma_f32_16x16x32_bf16 v[42:45], v[58:61], v[18:21], v[42:45]
	v_mfma_f32_16x16x32_bf16 v[46:49], v[62:65], v[18:21], v[46:49]
	v_mfma_f32_16x16x32_bf16 v[14:17], v[66:69], v[18:21], v[14:17]
	ds_read_b128 v[18:21], v150 offset:896
	ds_read_b128 v[66:69], v97 offset:5024
	s_waitcnt lgkmcnt(2)
	v_mfma_f32_16x16x32_bf16 v[22:25], v[70:73], v[238:241], v[22:25]
	v_mfma_f32_16x16x32_bf16 v[26:29], v[74:77], v[238:241], v[26:29]
	v_mfma_f32_16x16x32_bf16 v[30:33], v[78:81], v[238:241], v[30:33]
	v_mfma_f32_16x16x32_bf16 v[34:37], v[82:85], v[238:241], v[34:37]
	v_mfma_f32_16x16x32_bf16 v[38:41], v[50:53], v[238:241], v[38:41]
	v_mfma_f32_16x16x32_bf16 v[42:45], v[54:57], v[238:241], v[42:45]
	v_mfma_f32_16x16x32_bf16 v[46:49], v[58:61], v[238:241], v[46:49]
	v_mfma_f32_16x16x32_bf16 v[14:17], v[62:65], v[238:241], v[14:17]
	ds_read_b128 v[238:241], v150 offset:960
	ds_read_b128 v[62:65], v97 offset:5088
	s_waitcnt lgkmcnt(2)
	v_mfma_f32_16x16x32_bf16 v[22:25], v[66:69], v[18:21], v[22:25]
	v_mfma_f32_16x16x32_bf16 v[26:29], v[70:73], v[18:21], v[26:29]
	v_mfma_f32_16x16x32_bf16 v[30:33], v[74:77], v[18:21], v[30:33]
	v_mfma_f32_16x16x32_bf16 v[34:37], v[78:81], v[18:21], v[34:37]
	v_mfma_f32_16x16x32_bf16 v[38:41], v[82:85], v[18:21], v[38:41]
	v_mfma_f32_16x16x32_bf16 v[42:45], v[50:53], v[18:21], v[42:45]
	v_mfma_f32_16x16x32_bf16 v[46:49], v[54:57], v[18:21], v[46:49]
	v_mfma_f32_16x16x32_bf16 v[14:17], v[58:61], v[18:21], v[14:17]
	ds_read_b128 v[18:21], v150 offset:1024
	ds_read_b128 v[58:61], v97 offset:5152
	s_waitcnt lgkmcnt(2)
	v_mfma_f32_16x16x32_bf16 v[22:25], v[62:65], v[238:241], v[22:25]
	v_mfma_f32_16x16x32_bf16 v[26:29], v[66:69], v[238:241], v[26:29]
	v_mfma_f32_16x16x32_bf16 v[30:33], v[70:73], v[238:241], v[30:33]
	v_mfma_f32_16x16x32_bf16 v[34:37], v[74:77], v[238:241], v[34:37]
	v_mfma_f32_16x16x32_bf16 v[38:41], v[78:81], v[238:241], v[38:41]
	v_mfma_f32_16x16x32_bf16 v[42:45], v[82:85], v[238:241], v[42:45]
	v_mfma_f32_16x16x32_bf16 v[46:49], v[50:53], v[238:241], v[46:49]
	v_mfma_f32_16x16x32_bf16 v[14:17], v[54:57], v[238:241], v[14:17]
	ds_read_b128 v[238:241], v150 offset:1088
	ds_read_b128 v[54:57], v97 offset:5216
	s_waitcnt lgkmcnt(2)
	v_mfma_f32_16x16x32_bf16 v[22:25], v[58:61], v[18:21], v[22:25]
	v_mfma_f32_16x16x32_bf16 v[26:29], v[62:65], v[18:21], v[26:29]
	v_mfma_f32_16x16x32_bf16 v[30:33], v[66:69], v[18:21], v[30:33]
	v_mfma_f32_16x16x32_bf16 v[34:37], v[70:73], v[18:21], v[34:37]
	v_mfma_f32_16x16x32_bf16 v[38:41], v[74:77], v[18:21], v[38:41]
	v_mfma_f32_16x16x32_bf16 v[42:45], v[78:81], v[18:21], v[42:45]
	v_mfma_f32_16x16x32_bf16 v[46:49], v[82:85], v[18:21], v[46:49]
	v_mfma_f32_16x16x32_bf16 v[14:17], v[50:53], v[18:21], v[14:17]
	ds_read_b128 v[18:21], v150 offset:1152
	ds_read_b128 v[50:53], v97 offset:5280
	s_waitcnt lgkmcnt(2)
	v_mfma_f32_16x16x32_bf16 v[22:25], v[54:57], v[238:241], v[22:25]
	v_mfma_f32_16x16x32_bf16 v[26:29], v[58:61], v[238:241], v[26:29]
	v_mfma_f32_16x16x32_bf16 v[30:33], v[62:65], v[238:241], v[30:33]
	v_mfma_f32_16x16x32_bf16 v[34:37], v[66:69], v[238:241], v[34:37]
	v_mfma_f32_16x16x32_bf16 v[38:41], v[70:73], v[238:241], v[38:41]
	v_mfma_f32_16x16x32_bf16 v[42:45], v[74:77], v[238:241], v[42:45]
	v_mfma_f32_16x16x32_bf16 v[46:49], v[78:81], v[238:241], v[46:49]
	v_mfma_f32_16x16x32_bf16 v[14:17], v[82:85], v[238:241], v[14:17]
	ds_read_b128 v[238:241], v150 offset:1216
	ds_read_b128 v[82:85], v97 offset:5344
	s_waitcnt lgkmcnt(2)
	v_mfma_f32_16x16x32_bf16 v[22:25], v[50:53], v[18:21], v[22:25]
	v_mfma_f32_16x16x32_bf16 v[26:29], v[54:57], v[18:21], v[26:29]
	v_mfma_f32_16x16x32_bf16 v[30:33], v[58:61], v[18:21], v[30:33]
	v_mfma_f32_16x16x32_bf16 v[34:37], v[62:65], v[18:21], v[34:37]
	v_mfma_f32_16x16x32_bf16 v[38:41], v[66:69], v[18:21], v[38:41]
	v_mfma_f32_16x16x32_bf16 v[42:45], v[70:73], v[18:21], v[42:45]
	v_mfma_f32_16x16x32_bf16 v[46:49], v[74:77], v[18:21], v[46:49]
	v_mfma_f32_16x16x32_bf16 v[14:17], v[78:81], v[18:21], v[14:17]
	ds_read_b128 v[18:21], v150 offset:1280
	ds_read_b128 v[78:81], v97 offset:5408
	s_waitcnt lgkmcnt(2)
	v_mfma_f32_16x16x32_bf16 v[22:25], v[82:85], v[238:241], v[22:25]
	v_mfma_f32_16x16x32_bf16 v[26:29], v[50:53], v[238:241], v[26:29]
	v_mfma_f32_16x16x32_bf16 v[30:33], v[54:57], v[238:241], v[30:33]
	v_mfma_f32_16x16x32_bf16 v[34:37], v[58:61], v[238:241], v[34:37]
	v_mfma_f32_16x16x32_bf16 v[38:41], v[62:65], v[238:241], v[38:41]
	v_mfma_f32_16x16x32_bf16 v[42:45], v[66:69], v[238:241], v[42:45]
	v_mfma_f32_16x16x32_bf16 v[46:49], v[70:73], v[238:241], v[46:49]
	v_mfma_f32_16x16x32_bf16 v[14:17], v[74:77], v[238:241], v[14:17]
	ds_read_b128 v[238:241], v150 offset:1344
	ds_read_b128 v[74:77], v97 offset:5472
	s_waitcnt lgkmcnt(2)
	v_mfma_f32_16x16x32_bf16 v[22:25], v[78:81], v[18:21], v[22:25]
	v_mfma_f32_16x16x32_bf16 v[26:29], v[82:85], v[18:21], v[26:29]
	v_mfma_f32_16x16x32_bf16 v[30:33], v[50:53], v[18:21], v[30:33]
	v_mfma_f32_16x16x32_bf16 v[34:37], v[54:57], v[18:21], v[34:37]
	v_mfma_f32_16x16x32_bf16 v[38:41], v[58:61], v[18:21], v[38:41]
	v_mfma_f32_16x16x32_bf16 v[42:45], v[62:65], v[18:21], v[42:45]
	v_mfma_f32_16x16x32_bf16 v[46:49], v[66:69], v[18:21], v[46:49]
	v_mfma_f32_16x16x32_bf16 v[14:17], v[70:73], v[18:21], v[14:17]
	ds_read_b128 v[18:21], v150 offset:1408
	ds_read_b128 v[70:73], v97 offset:5536
	s_waitcnt lgkmcnt(2)
	v_mfma_f32_16x16x32_bf16 v[22:25], v[74:77], v[238:241], v[22:25]
	v_mfma_f32_16x16x32_bf16 v[26:29], v[78:81], v[238:241], v[26:29]
	v_mfma_f32_16x16x32_bf16 v[30:33], v[82:85], v[238:241], v[30:33]
	v_mfma_f32_16x16x32_bf16 v[34:37], v[50:53], v[238:241], v[34:37]
	v_mfma_f32_16x16x32_bf16 v[38:41], v[54:57], v[238:241], v[38:41]
	v_mfma_f32_16x16x32_bf16 v[42:45], v[58:61], v[238:241], v[42:45]
	v_mfma_f32_16x16x32_bf16 v[46:49], v[62:65], v[238:241], v[46:49]
	v_mfma_f32_16x16x32_bf16 v[14:17], v[66:69], v[238:241], v[14:17]
	ds_read_b128 v[238:241], v150 offset:1472
	ds_read_b128 v[66:69], v97 offset:5600
	s_waitcnt lgkmcnt(2)
	v_mfma_f32_16x16x32_bf16 v[22:25], v[70:73], v[18:21], v[22:25]
	v_mfma_f32_16x16x32_bf16 v[26:29], v[74:77], v[18:21], v[26:29]
	v_mfma_f32_16x16x32_bf16 v[30:33], v[78:81], v[18:21], v[30:33]
	v_mfma_f32_16x16x32_bf16 v[34:37], v[82:85], v[18:21], v[34:37]
	v_mfma_f32_16x16x32_bf16 v[38:41], v[50:53], v[18:21], v[38:41]
	v_mfma_f32_16x16x32_bf16 v[42:45], v[54:57], v[18:21], v[42:45]
	v_mfma_f32_16x16x32_bf16 v[46:49], v[58:61], v[18:21], v[46:49]
	v_mfma_f32_16x16x32_bf16 v[14:17], v[62:65], v[18:21], v[14:17]
	ds_read_b128 v[18:21], v150 offset:1536
	ds_read_b128 v[62:65], v97 offset:5664
	s_waitcnt lgkmcnt(2)
	v_mfma_f32_16x16x32_bf16 v[22:25], v[66:69], v[238:241], v[22:25]
	v_mfma_f32_16x16x32_bf16 v[26:29], v[70:73], v[238:241], v[26:29]
	v_mfma_f32_16x16x32_bf16 v[30:33], v[74:77], v[238:241], v[30:33]
	v_mfma_f32_16x16x32_bf16 v[34:37], v[78:81], v[238:241], v[34:37]
	v_mfma_f32_16x16x32_bf16 v[38:41], v[82:85], v[238:241], v[38:41]
	v_mfma_f32_16x16x32_bf16 v[42:45], v[50:53], v[238:241], v[42:45]
	v_mfma_f32_16x16x32_bf16 v[46:49], v[54:57], v[238:241], v[46:49]
	v_mfma_f32_16x16x32_bf16 v[14:17], v[58:61], v[238:241], v[14:17]
	ds_read_b128 v[238:241], v150 offset:1600
	ds_read_b128 v[58:61], v97 offset:5728
	s_waitcnt lgkmcnt(2)
	v_mfma_f32_16x16x32_bf16 v[22:25], v[62:65], v[18:21], v[22:25]
	v_mfma_f32_16x16x32_bf16 v[26:29], v[66:69], v[18:21], v[26:29]
	v_mfma_f32_16x16x32_bf16 v[30:33], v[70:73], v[18:21], v[30:33]
	v_mfma_f32_16x16x32_bf16 v[34:37], v[74:77], v[18:21], v[34:37]
	v_mfma_f32_16x16x32_bf16 v[38:41], v[78:81], v[18:21], v[38:41]
	v_mfma_f32_16x16x32_bf16 v[42:45], v[82:85], v[18:21], v[42:45]
	v_mfma_f32_16x16x32_bf16 v[46:49], v[50:53], v[18:21], v[46:49]
	v_mfma_f32_16x16x32_bf16 v[14:17], v[54:57], v[18:21], v[14:17]
	ds_read_b128 v[18:21], v150 offset:1664
	ds_read_b128 v[54:57], v97 offset:5792
	s_waitcnt lgkmcnt(2)
	v_mfma_f32_16x16x32_bf16 v[22:25], v[58:61], v[238:241], v[22:25]
	v_mfma_f32_16x16x32_bf16 v[26:29], v[62:65], v[238:241], v[26:29]
	v_mfma_f32_16x16x32_bf16 v[30:33], v[66:69], v[238:241], v[30:33]
	v_mfma_f32_16x16x32_bf16 v[34:37], v[70:73], v[238:241], v[34:37]
	v_mfma_f32_16x16x32_bf16 v[38:41], v[74:77], v[238:241], v[38:41]
	v_mfma_f32_16x16x32_bf16 v[42:45], v[78:81], v[238:241], v[42:45]
	v_mfma_f32_16x16x32_bf16 v[46:49], v[82:85], v[238:241], v[46:49]
	v_mfma_f32_16x16x32_bf16 v[14:17], v[50:53], v[238:241], v[14:17]
	ds_read_b128 v[238:241], v150 offset:1728
	ds_read_b128 v[50:53], v97 offset:5856
	s_waitcnt lgkmcnt(2)
	v_mfma_f32_16x16x32_bf16 v[22:25], v[54:57], v[18:21], v[22:25]
	v_mfma_f32_16x16x32_bf16 v[26:29], v[58:61], v[18:21], v[26:29]
	v_mfma_f32_16x16x32_bf16 v[30:33], v[62:65], v[18:21], v[30:33]
	v_mfma_f32_16x16x32_bf16 v[34:37], v[66:69], v[18:21], v[34:37]
	v_mfma_f32_16x16x32_bf16 v[38:41], v[70:73], v[18:21], v[38:41]
	v_mfma_f32_16x16x32_bf16 v[42:45], v[74:77], v[18:21], v[42:45]
	v_mfma_f32_16x16x32_bf16 v[46:49], v[78:81], v[18:21], v[46:49]
	v_mfma_f32_16x16x32_bf16 v[14:17], v[82:85], v[18:21], v[14:17]
	ds_read_b128 v[18:21], v150 offset:1792
	ds_read_b128 v[82:85], v97 offset:5920
	s_waitcnt lgkmcnt(2)
	v_mfma_f32_16x16x32_bf16 v[22:25], v[50:53], v[238:241], v[22:25]
	v_mfma_f32_16x16x32_bf16 v[26:29], v[54:57], v[238:241], v[26:29]
	v_mfma_f32_16x16x32_bf16 v[30:33], v[58:61], v[238:241], v[30:33]
	v_mfma_f32_16x16x32_bf16 v[34:37], v[62:65], v[238:241], v[34:37]
	v_mfma_f32_16x16x32_bf16 v[38:41], v[66:69], v[238:241], v[38:41]
	v_mfma_f32_16x16x32_bf16 v[42:45], v[70:73], v[238:241], v[42:45]
	v_mfma_f32_16x16x32_bf16 v[46:49], v[74:77], v[238:241], v[46:49]
	v_mfma_f32_16x16x32_bf16 v[14:17], v[78:81], v[238:241], v[14:17]
	ds_read_b128 v[238:241], v150 offset:1856
	ds_read_b128 v[78:81], v97 offset:5984
	s_waitcnt lgkmcnt(2)
	v_mfma_f32_16x16x32_bf16 v[22:25], v[82:85], v[18:21], v[22:25]
	v_mfma_f32_16x16x32_bf16 v[26:29], v[50:53], v[18:21], v[26:29]
	v_mfma_f32_16x16x32_bf16 v[30:33], v[54:57], v[18:21], v[30:33]
	v_mfma_f32_16x16x32_bf16 v[34:37], v[58:61], v[18:21], v[34:37]
	v_mfma_f32_16x16x32_bf16 v[38:41], v[62:65], v[18:21], v[38:41]
	v_mfma_f32_16x16x32_bf16 v[42:45], v[66:69], v[18:21], v[42:45]
	v_mfma_f32_16x16x32_bf16 v[46:49], v[70:73], v[18:21], v[46:49]
	v_mfma_f32_16x16x32_bf16 v[14:17], v[74:77], v[18:21], v[14:17]
	ds_read_b128 v[18:21], v150 offset:1920
	ds_read_b128 v[74:77], v97 offset:6048
	s_waitcnt lgkmcnt(2)
	v_mfma_f32_16x16x32_bf16 v[22:25], v[78:81], v[238:241], v[22:25]
	v_mfma_f32_16x16x32_bf16 v[26:29], v[82:85], v[238:241], v[26:29]
	v_mfma_f32_16x16x32_bf16 v[30:33], v[50:53], v[238:241], v[30:33]
	v_mfma_f32_16x16x32_bf16 v[34:37], v[54:57], v[238:241], v[34:37]
	v_mfma_f32_16x16x32_bf16 v[38:41], v[58:61], v[238:241], v[38:41]
	v_mfma_f32_16x16x32_bf16 v[42:45], v[62:65], v[238:241], v[42:45]
	v_mfma_f32_16x16x32_bf16 v[46:49], v[66:69], v[238:241], v[46:49]
	v_mfma_f32_16x16x32_bf16 v[14:17], v[70:73], v[238:241], v[14:17]
	ds_read_b128 v[238:241], v150 offset:1984
	ds_read_b128 v[70:73], v97 offset:6112
	s_waitcnt lgkmcnt(2)
	v_mfma_f32_16x16x32_bf16 v[22:25], v[74:77], v[18:21], v[22:25]
	v_mfma_f32_16x16x32_bf16 v[26:29], v[78:81], v[18:21], v[26:29]
	v_mfma_f32_16x16x32_bf16 v[30:33], v[82:85], v[18:21], v[30:33]
	v_mfma_f32_16x16x32_bf16 v[34:37], v[50:53], v[18:21], v[34:37]
	v_mfma_f32_16x16x32_bf16 v[38:41], v[54:57], v[18:21], v[38:41]
	v_mfma_f32_16x16x32_bf16 v[42:45], v[58:61], v[18:21], v[42:45]
	v_mfma_f32_16x16x32_bf16 v[46:49], v[62:65], v[18:21], v[46:49]
	v_mfma_f32_16x16x32_bf16 v[14:17], v[66:69], v[18:21], v[14:17]
	ds_read_b128 v[18:21], v150 offset:2048
	ds_read_b128 v[66:69], v97 offset:6176
	s_waitcnt lgkmcnt(2)
	v_mfma_f32_16x16x32_bf16 v[22:25], v[70:73], v[238:241], v[22:25]
	v_mfma_f32_16x16x32_bf16 v[26:29], v[74:77], v[238:241], v[26:29]
	v_mfma_f32_16x16x32_bf16 v[30:33], v[78:81], v[238:241], v[30:33]
	v_mfma_f32_16x16x32_bf16 v[34:37], v[82:85], v[238:241], v[34:37]
	v_mfma_f32_16x16x32_bf16 v[38:41], v[50:53], v[238:241], v[38:41]
	v_mfma_f32_16x16x32_bf16 v[42:45], v[54:57], v[238:241], v[42:45]
	v_mfma_f32_16x16x32_bf16 v[46:49], v[58:61], v[238:241], v[46:49]
	v_mfma_f32_16x16x32_bf16 v[14:17], v[62:65], v[238:241], v[14:17]
	ds_read_b128 v[238:241], v150 offset:2112
	ds_read_b128 v[62:65], v97 offset:6240
	s_waitcnt lgkmcnt(2)
	v_mfma_f32_16x16x32_bf16 v[22:25], v[66:69], v[18:21], v[22:25]
	v_mfma_f32_16x16x32_bf16 v[26:29], v[70:73], v[18:21], v[26:29]
	v_mfma_f32_16x16x32_bf16 v[30:33], v[74:77], v[18:21], v[30:33]
	v_mfma_f32_16x16x32_bf16 v[34:37], v[78:81], v[18:21], v[34:37]
	v_mfma_f32_16x16x32_bf16 v[38:41], v[82:85], v[18:21], v[38:41]
	v_mfma_f32_16x16x32_bf16 v[42:45], v[50:53], v[18:21], v[42:45]
	v_mfma_f32_16x16x32_bf16 v[46:49], v[54:57], v[18:21], v[46:49]
	v_mfma_f32_16x16x32_bf16 v[14:17], v[58:61], v[18:21], v[14:17]
	ds_read_b128 v[18:21], v150 offset:2176
	ds_read_b128 v[58:61], v97 offset:6304
	s_waitcnt lgkmcnt(2)
	v_mfma_f32_16x16x32_bf16 v[22:25], v[62:65], v[238:241], v[22:25]
	v_mfma_f32_16x16x32_bf16 v[26:29], v[66:69], v[238:241], v[26:29]
	v_mfma_f32_16x16x32_bf16 v[30:33], v[70:73], v[238:241], v[30:33]
	v_mfma_f32_16x16x32_bf16 v[34:37], v[74:77], v[238:241], v[34:37]
	v_mfma_f32_16x16x32_bf16 v[38:41], v[78:81], v[238:241], v[38:41]
	v_mfma_f32_16x16x32_bf16 v[42:45], v[82:85], v[238:241], v[42:45]
	v_mfma_f32_16x16x32_bf16 v[46:49], v[50:53], v[238:241], v[46:49]
	v_mfma_f32_16x16x32_bf16 v[14:17], v[54:57], v[238:241], v[14:17]
	ds_read_b128 v[238:241], v150 offset:2240
	ds_read_b128 v[54:57], v97 offset:6368
	s_waitcnt lgkmcnt(2)
	v_mfma_f32_16x16x32_bf16 v[22:25], v[58:61], v[18:21], v[22:25]
	v_mfma_f32_16x16x32_bf16 v[26:29], v[62:65], v[18:21], v[26:29]
	v_mfma_f32_16x16x32_bf16 v[30:33], v[66:69], v[18:21], v[30:33]
	v_mfma_f32_16x16x32_bf16 v[34:37], v[70:73], v[18:21], v[34:37]
	v_mfma_f32_16x16x32_bf16 v[38:41], v[74:77], v[18:21], v[38:41]
	v_mfma_f32_16x16x32_bf16 v[42:45], v[78:81], v[18:21], v[42:45]
	v_mfma_f32_16x16x32_bf16 v[46:49], v[82:85], v[18:21], v[46:49]
	v_mfma_f32_16x16x32_bf16 v[14:17], v[50:53], v[18:21], v[14:17]
	ds_read_b128 v[18:21], v150 offset:2304
	ds_read_b128 v[50:53], v97 offset:6432
	s_waitcnt lgkmcnt(2)
	v_mfma_f32_16x16x32_bf16 v[22:25], v[54:57], v[238:241], v[22:25]
	v_mfma_f32_16x16x32_bf16 v[26:29], v[58:61], v[238:241], v[26:29]
	v_mfma_f32_16x16x32_bf16 v[30:33], v[62:65], v[238:241], v[30:33]
	v_mfma_f32_16x16x32_bf16 v[34:37], v[66:69], v[238:241], v[34:37]
	v_mfma_f32_16x16x32_bf16 v[38:41], v[70:73], v[238:241], v[38:41]
	v_mfma_f32_16x16x32_bf16 v[42:45], v[74:77], v[238:241], v[42:45]
	v_mfma_f32_16x16x32_bf16 v[46:49], v[78:81], v[238:241], v[46:49]
	v_mfma_f32_16x16x32_bf16 v[14:17], v[82:85], v[238:241], v[14:17]
	ds_read_b128 v[238:241], v150 offset:2368
	ds_read_b128 v[82:85], v97 offset:6496
	s_waitcnt lgkmcnt(2)
	v_mfma_f32_16x16x32_bf16 v[22:25], v[50:53], v[18:21], v[22:25]
	v_mfma_f32_16x16x32_bf16 v[26:29], v[54:57], v[18:21], v[26:29]
	v_mfma_f32_16x16x32_bf16 v[30:33], v[58:61], v[18:21], v[30:33]
	v_mfma_f32_16x16x32_bf16 v[34:37], v[62:65], v[18:21], v[34:37]
	v_mfma_f32_16x16x32_bf16 v[38:41], v[66:69], v[18:21], v[38:41]
	v_mfma_f32_16x16x32_bf16 v[42:45], v[70:73], v[18:21], v[42:45]
	v_mfma_f32_16x16x32_bf16 v[46:49], v[74:77], v[18:21], v[46:49]
	v_mfma_f32_16x16x32_bf16 v[14:17], v[78:81], v[18:21], v[14:17]
	ds_read_b128 v[18:21], v150 offset:2432
	ds_read_b128 v[78:81], v97 offset:6560
	s_waitcnt lgkmcnt(2)
	v_mfma_f32_16x16x32_bf16 v[22:25], v[82:85], v[238:241], v[22:25]
	v_mfma_f32_16x16x32_bf16 v[26:29], v[50:53], v[238:241], v[26:29]
	v_mfma_f32_16x16x32_bf16 v[30:33], v[54:57], v[238:241], v[30:33]
	v_mfma_f32_16x16x32_bf16 v[34:37], v[58:61], v[238:241], v[34:37]
	v_mfma_f32_16x16x32_bf16 v[38:41], v[62:65], v[238:241], v[38:41]
	v_mfma_f32_16x16x32_bf16 v[42:45], v[66:69], v[238:241], v[42:45]
	v_mfma_f32_16x16x32_bf16 v[46:49], v[70:73], v[238:241], v[46:49]
	v_mfma_f32_16x16x32_bf16 v[14:17], v[74:77], v[238:241], v[14:17]
	ds_read_b128 v[238:241], v150 offset:2496
	ds_read_b128 v[74:77], v97 offset:6624
	s_waitcnt lgkmcnt(2)
	v_mfma_f32_16x16x32_bf16 v[22:25], v[78:81], v[18:21], v[22:25]
	v_mfma_f32_16x16x32_bf16 v[26:29], v[82:85], v[18:21], v[26:29]
	v_mfma_f32_16x16x32_bf16 v[30:33], v[50:53], v[18:21], v[30:33]
	v_mfma_f32_16x16x32_bf16 v[34:37], v[54:57], v[18:21], v[34:37]
	v_mfma_f32_16x16x32_bf16 v[38:41], v[58:61], v[18:21], v[38:41]
	v_mfma_f32_16x16x32_bf16 v[42:45], v[62:65], v[18:21], v[42:45]
	v_mfma_f32_16x16x32_bf16 v[46:49], v[66:69], v[18:21], v[46:49]
	v_mfma_f32_16x16x32_bf16 v[14:17], v[70:73], v[18:21], v[14:17]
	ds_read_b128 v[18:21], v150 offset:2560
	ds_read_b128 v[70:73], v97 offset:6688
	s_waitcnt lgkmcnt(2)
	v_mfma_f32_16x16x32_bf16 v[22:25], v[74:77], v[238:241], v[22:25]
	v_mfma_f32_16x16x32_bf16 v[26:29], v[78:81], v[238:241], v[26:29]
	v_mfma_f32_16x16x32_bf16 v[30:33], v[82:85], v[238:241], v[30:33]
	v_mfma_f32_16x16x32_bf16 v[34:37], v[50:53], v[238:241], v[34:37]
	v_mfma_f32_16x16x32_bf16 v[38:41], v[54:57], v[238:241], v[38:41]
	v_mfma_f32_16x16x32_bf16 v[42:45], v[58:61], v[238:241], v[42:45]
	v_mfma_f32_16x16x32_bf16 v[46:49], v[62:65], v[238:241], v[46:49]
	v_mfma_f32_16x16x32_bf16 v[14:17], v[66:69], v[238:241], v[14:17]
	ds_read_b128 v[238:241], v150 offset:2624
	ds_read_b128 v[66:69], v97 offset:6752
	s_waitcnt lgkmcnt(2)
	v_mfma_f32_16x16x32_bf16 v[22:25], v[70:73], v[18:21], v[22:25]
	v_mfma_f32_16x16x32_bf16 v[26:29], v[74:77], v[18:21], v[26:29]
	v_mfma_f32_16x16x32_bf16 v[30:33], v[78:81], v[18:21], v[30:33]
	v_mfma_f32_16x16x32_bf16 v[34:37], v[82:85], v[18:21], v[34:37]
	v_mfma_f32_16x16x32_bf16 v[38:41], v[50:53], v[18:21], v[38:41]
	v_mfma_f32_16x16x32_bf16 v[42:45], v[54:57], v[18:21], v[42:45]
	v_mfma_f32_16x16x32_bf16 v[46:49], v[58:61], v[18:21], v[46:49]
	v_mfma_f32_16x16x32_bf16 v[14:17], v[62:65], v[18:21], v[14:17]
	ds_read_b128 v[18:21], v150 offset:2688
	ds_read_b128 v[62:65], v97 offset:6816
	s_waitcnt lgkmcnt(2)
	v_mfma_f32_16x16x32_bf16 v[22:25], v[66:69], v[238:241], v[22:25]
	v_mfma_f32_16x16x32_bf16 v[26:29], v[70:73], v[238:241], v[26:29]
	v_mfma_f32_16x16x32_bf16 v[30:33], v[74:77], v[238:241], v[30:33]
	v_mfma_f32_16x16x32_bf16 v[34:37], v[78:81], v[238:241], v[34:37]
	v_mfma_f32_16x16x32_bf16 v[38:41], v[82:85], v[238:241], v[38:41]
	v_mfma_f32_16x16x32_bf16 v[42:45], v[50:53], v[238:241], v[42:45]
	v_mfma_f32_16x16x32_bf16 v[46:49], v[54:57], v[238:241], v[46:49]
	v_mfma_f32_16x16x32_bf16 v[14:17], v[58:61], v[238:241], v[14:17]
	ds_read_b128 v[238:241], v150 offset:2752
	ds_read_b128 v[58:61], v97 offset:6880
	s_waitcnt lgkmcnt(2)
	v_mfma_f32_16x16x32_bf16 v[22:25], v[62:65], v[18:21], v[22:25]
	v_mfma_f32_16x16x32_bf16 v[26:29], v[66:69], v[18:21], v[26:29]
	v_mfma_f32_16x16x32_bf16 v[30:33], v[70:73], v[18:21], v[30:33]
	v_mfma_f32_16x16x32_bf16 v[34:37], v[74:77], v[18:21], v[34:37]
	v_mfma_f32_16x16x32_bf16 v[38:41], v[78:81], v[18:21], v[38:41]
	v_mfma_f32_16x16x32_bf16 v[42:45], v[82:85], v[18:21], v[42:45]
	v_mfma_f32_16x16x32_bf16 v[46:49], v[50:53], v[18:21], v[46:49]
	v_mfma_f32_16x16x32_bf16 v[14:17], v[54:57], v[18:21], v[14:17]
	ds_read_b128 v[18:21], v150 offset:2816
	ds_read_b128 v[54:57], v97 offset:6944
	s_waitcnt lgkmcnt(2)
	v_mfma_f32_16x16x32_bf16 v[22:25], v[58:61], v[238:241], v[22:25]
	v_mfma_f32_16x16x32_bf16 v[26:29], v[62:65], v[238:241], v[26:29]
	v_mfma_f32_16x16x32_bf16 v[30:33], v[66:69], v[238:241], v[30:33]
	v_mfma_f32_16x16x32_bf16 v[34:37], v[70:73], v[238:241], v[34:37]
	v_mfma_f32_16x16x32_bf16 v[38:41], v[74:77], v[238:241], v[38:41]
	v_mfma_f32_16x16x32_bf16 v[42:45], v[78:81], v[238:241], v[42:45]
	v_mfma_f32_16x16x32_bf16 v[46:49], v[82:85], v[238:241], v[46:49]
	v_mfma_f32_16x16x32_bf16 v[14:17], v[50:53], v[238:241], v[14:17]
	ds_read_b128 v[238:241], v150 offset:2880
	ds_read_b128 v[50:53], v97 offset:7008
	s_waitcnt lgkmcnt(2)
	v_mfma_f32_16x16x32_bf16 v[22:25], v[54:57], v[18:21], v[22:25]
	v_mfma_f32_16x16x32_bf16 v[26:29], v[58:61], v[18:21], v[26:29]
	v_mfma_f32_16x16x32_bf16 v[30:33], v[62:65], v[18:21], v[30:33]
	v_mfma_f32_16x16x32_bf16 v[34:37], v[66:69], v[18:21], v[34:37]
	v_mfma_f32_16x16x32_bf16 v[38:41], v[70:73], v[18:21], v[38:41]
	v_mfma_f32_16x16x32_bf16 v[42:45], v[74:77], v[18:21], v[42:45]
	v_mfma_f32_16x16x32_bf16 v[46:49], v[78:81], v[18:21], v[46:49]
	v_mfma_f32_16x16x32_bf16 v[14:17], v[82:85], v[18:21], v[14:17]
	ds_read_b128 v[18:21], v150 offset:2944
	ds_read_b128 v[82:85], v97 offset:7072
	s_waitcnt lgkmcnt(2)
	v_mfma_f32_16x16x32_bf16 v[22:25], v[50:53], v[238:241], v[22:25]
	v_mfma_f32_16x16x32_bf16 v[26:29], v[54:57], v[238:241], v[26:29]
	v_mfma_f32_16x16x32_bf16 v[30:33], v[58:61], v[238:241], v[30:33]
	v_mfma_f32_16x16x32_bf16 v[34:37], v[62:65], v[238:241], v[34:37]
	v_mfma_f32_16x16x32_bf16 v[38:41], v[66:69], v[238:241], v[38:41]
	v_mfma_f32_16x16x32_bf16 v[42:45], v[70:73], v[238:241], v[42:45]
	v_mfma_f32_16x16x32_bf16 v[46:49], v[74:77], v[238:241], v[46:49]
	v_mfma_f32_16x16x32_bf16 v[14:17], v[78:81], v[238:241], v[14:17]
	ds_read_b128 v[238:241], v150 offset:3008
	ds_read_b128 v[78:81], v97 offset:7136
	s_waitcnt lgkmcnt(2)
	v_mfma_f32_16x16x32_bf16 v[22:25], v[82:85], v[18:21], v[22:25]
	v_mfma_f32_16x16x32_bf16 v[26:29], v[50:53], v[18:21], v[26:29]
	v_mfma_f32_16x16x32_bf16 v[30:33], v[54:57], v[18:21], v[30:33]
	v_mfma_f32_16x16x32_bf16 v[34:37], v[58:61], v[18:21], v[34:37]
	v_mfma_f32_16x16x32_bf16 v[38:41], v[62:65], v[18:21], v[38:41]
	v_mfma_f32_16x16x32_bf16 v[42:45], v[66:69], v[18:21], v[42:45]
	v_mfma_f32_16x16x32_bf16 v[46:49], v[70:73], v[18:21], v[46:49]
	v_mfma_f32_16x16x32_bf16 v[14:17], v[74:77], v[18:21], v[14:17]
	ds_read_b128 v[18:21], v150 offset:3072
	ds_read_b128 v[74:77], v97 offset:7200
	s_waitcnt lgkmcnt(2)
	v_mfma_f32_16x16x32_bf16 v[22:25], v[78:81], v[238:241], v[22:25]
	v_mfma_f32_16x16x32_bf16 v[26:29], v[82:85], v[238:241], v[26:29]
	v_mfma_f32_16x16x32_bf16 v[30:33], v[50:53], v[238:241], v[30:33]
	v_mfma_f32_16x16x32_bf16 v[34:37], v[54:57], v[238:241], v[34:37]
	v_mfma_f32_16x16x32_bf16 v[38:41], v[58:61], v[238:241], v[38:41]
	v_mfma_f32_16x16x32_bf16 v[42:45], v[62:65], v[238:241], v[42:45]
	v_mfma_f32_16x16x32_bf16 v[46:49], v[66:69], v[238:241], v[46:49]
	v_mfma_f32_16x16x32_bf16 v[14:17], v[70:73], v[238:241], v[14:17]
	ds_read_b128 v[238:241], v150 offset:3136
	ds_read_b128 v[70:73], v97 offset:7264
	s_waitcnt lgkmcnt(2)
	v_mfma_f32_16x16x32_bf16 v[22:25], v[74:77], v[18:21], v[22:25]
	v_mfma_f32_16x16x32_bf16 v[26:29], v[78:81], v[18:21], v[26:29]
	v_mfma_f32_16x16x32_bf16 v[30:33], v[82:85], v[18:21], v[30:33]
	v_mfma_f32_16x16x32_bf16 v[34:37], v[50:53], v[18:21], v[34:37]
	v_mfma_f32_16x16x32_bf16 v[38:41], v[54:57], v[18:21], v[38:41]
	v_mfma_f32_16x16x32_bf16 v[42:45], v[58:61], v[18:21], v[42:45]
	v_mfma_f32_16x16x32_bf16 v[46:49], v[62:65], v[18:21], v[46:49]
	v_mfma_f32_16x16x32_bf16 v[14:17], v[66:69], v[18:21], v[14:17]
	ds_read_b128 v[18:21], v150 offset:3200
	ds_read_b128 v[66:69], v97 offset:7328
	s_waitcnt lgkmcnt(2)
	v_mfma_f32_16x16x32_bf16 v[22:25], v[70:73], v[238:241], v[22:25]
	v_mfma_f32_16x16x32_bf16 v[26:29], v[74:77], v[238:241], v[26:29]
	v_mfma_f32_16x16x32_bf16 v[30:33], v[78:81], v[238:241], v[30:33]
	v_mfma_f32_16x16x32_bf16 v[34:37], v[82:85], v[238:241], v[34:37]
	v_mfma_f32_16x16x32_bf16 v[38:41], v[50:53], v[238:241], v[38:41]
	v_mfma_f32_16x16x32_bf16 v[42:45], v[54:57], v[238:241], v[42:45]
	v_mfma_f32_16x16x32_bf16 v[46:49], v[58:61], v[238:241], v[46:49]
	v_mfma_f32_16x16x32_bf16 v[14:17], v[62:65], v[238:241], v[14:17]
	ds_read_b128 v[238:241], v150 offset:3264
	ds_read_b128 v[62:65], v97 offset:7392
	s_waitcnt lgkmcnt(2)
	v_mfma_f32_16x16x32_bf16 v[22:25], v[66:69], v[18:21], v[22:25]
	v_mfma_f32_16x16x32_bf16 v[26:29], v[70:73], v[18:21], v[26:29]
	v_mfma_f32_16x16x32_bf16 v[30:33], v[74:77], v[18:21], v[30:33]
	v_mfma_f32_16x16x32_bf16 v[34:37], v[78:81], v[18:21], v[34:37]
	v_mfma_f32_16x16x32_bf16 v[38:41], v[82:85], v[18:21], v[38:41]
	v_mfma_f32_16x16x32_bf16 v[42:45], v[50:53], v[18:21], v[42:45]
	v_mfma_f32_16x16x32_bf16 v[46:49], v[54:57], v[18:21], v[46:49]
	v_mfma_f32_16x16x32_bf16 v[14:17], v[58:61], v[18:21], v[14:17]
	ds_read_b128 v[18:21], v150 offset:3328
	ds_read_b128 v[58:61], v97 offset:7456
	s_waitcnt lgkmcnt(2)
	v_mfma_f32_16x16x32_bf16 v[22:25], v[62:65], v[238:241], v[22:25]
	v_mfma_f32_16x16x32_bf16 v[26:29], v[66:69], v[238:241], v[26:29]
	v_mfma_f32_16x16x32_bf16 v[30:33], v[70:73], v[238:241], v[30:33]
	v_mfma_f32_16x16x32_bf16 v[34:37], v[74:77], v[238:241], v[34:37]
	v_mfma_f32_16x16x32_bf16 v[38:41], v[78:81], v[238:241], v[38:41]
	v_mfma_f32_16x16x32_bf16 v[42:45], v[82:85], v[238:241], v[42:45]
	v_mfma_f32_16x16x32_bf16 v[46:49], v[50:53], v[238:241], v[46:49]
	v_mfma_f32_16x16x32_bf16 v[14:17], v[54:57], v[238:241], v[14:17]
	ds_read_b128 v[238:241], v150 offset:3392
	ds_read_b128 v[54:57], v97 offset:7520
	s_waitcnt lgkmcnt(2)
	v_mfma_f32_16x16x32_bf16 v[22:25], v[58:61], v[18:21], v[22:25]
	v_mfma_f32_16x16x32_bf16 v[26:29], v[62:65], v[18:21], v[26:29]
	v_mfma_f32_16x16x32_bf16 v[30:33], v[66:69], v[18:21], v[30:33]
	v_mfma_f32_16x16x32_bf16 v[34:37], v[70:73], v[18:21], v[34:37]
	v_mfma_f32_16x16x32_bf16 v[38:41], v[74:77], v[18:21], v[38:41]
	v_mfma_f32_16x16x32_bf16 v[42:45], v[78:81], v[18:21], v[42:45]
	v_mfma_f32_16x16x32_bf16 v[46:49], v[82:85], v[18:21], v[46:49]
	v_mfma_f32_16x16x32_bf16 v[14:17], v[50:53], v[18:21], v[14:17]
	ds_read_b128 v[18:21], v150 offset:3456
	ds_read_b128 v[50:53], v97 offset:7584
	s_waitcnt lgkmcnt(2)
	v_mfma_f32_16x16x32_bf16 v[22:25], v[54:57], v[238:241], v[22:25]
	v_mfma_f32_16x16x32_bf16 v[26:29], v[58:61], v[238:241], v[26:29]
	v_mfma_f32_16x16x32_bf16 v[30:33], v[62:65], v[238:241], v[30:33]
	v_mfma_f32_16x16x32_bf16 v[34:37], v[66:69], v[238:241], v[34:37]
	v_mfma_f32_16x16x32_bf16 v[38:41], v[70:73], v[238:241], v[38:41]
	v_mfma_f32_16x16x32_bf16 v[42:45], v[74:77], v[238:241], v[42:45]
	v_mfma_f32_16x16x32_bf16 v[46:49], v[78:81], v[238:241], v[46:49]
	v_mfma_f32_16x16x32_bf16 v[14:17], v[82:85], v[238:241], v[14:17]
	ds_read_b128 v[238:241], v150 offset:3520
	ds_read_b128 v[82:85], v97 offset:7648
	s_waitcnt lgkmcnt(2)
	v_mfma_f32_16x16x32_bf16 v[22:25], v[50:53], v[18:21], v[22:25]
	v_mfma_f32_16x16x32_bf16 v[26:29], v[54:57], v[18:21], v[26:29]
	v_mfma_f32_16x16x32_bf16 v[30:33], v[58:61], v[18:21], v[30:33]
	v_mfma_f32_16x16x32_bf16 v[34:37], v[62:65], v[18:21], v[34:37]
	v_mfma_f32_16x16x32_bf16 v[38:41], v[66:69], v[18:21], v[38:41]
	v_mfma_f32_16x16x32_bf16 v[42:45], v[70:73], v[18:21], v[42:45]
	v_mfma_f32_16x16x32_bf16 v[46:49], v[74:77], v[18:21], v[46:49]
	v_mfma_f32_16x16x32_bf16 v[14:17], v[78:81], v[18:21], v[14:17]
	ds_read_b128 v[18:21], v150 offset:3584
	ds_read_b128 v[78:81], v97 offset:7712
	s_waitcnt lgkmcnt(2)
	v_mfma_f32_16x16x32_bf16 v[22:25], v[82:85], v[238:241], v[22:25]
	v_mfma_f32_16x16x32_bf16 v[26:29], v[50:53], v[238:241], v[26:29]
	v_mfma_f32_16x16x32_bf16 v[30:33], v[54:57], v[238:241], v[30:33]
	v_mfma_f32_16x16x32_bf16 v[34:37], v[58:61], v[238:241], v[34:37]
	v_mfma_f32_16x16x32_bf16 v[38:41], v[62:65], v[238:241], v[38:41]
	v_mfma_f32_16x16x32_bf16 v[42:45], v[66:69], v[238:241], v[42:45]
	v_mfma_f32_16x16x32_bf16 v[46:49], v[70:73], v[238:241], v[46:49]
	v_mfma_f32_16x16x32_bf16 v[14:17], v[74:77], v[238:241], v[14:17]
	ds_read_b128 v[74:77], v97 offset:7776
	s_waitcnt lgkmcnt(1)
	v_mfma_f32_16x16x32_bf16 v[22:25], v[78:81], v[18:21], v[22:25]
	v_mfma_f32_16x16x32_bf16 v[26:29], v[82:85], v[18:21], v[26:29]
	v_mfma_f32_16x16x32_bf16 v[30:33], v[50:53], v[18:21], v[30:33]
	v_mfma_f32_16x16x32_bf16 v[34:37], v[54:57], v[18:21], v[34:37]
	v_mfma_f32_16x16x32_bf16 v[38:41], v[58:61], v[18:21], v[38:41]
	v_mfma_f32_16x16x32_bf16 v[42:45], v[62:65], v[18:21], v[42:45]
	v_mfma_f32_16x16x32_bf16 v[46:49], v[66:69], v[18:21], v[46:49]
	v_mfma_f32_16x16x32_bf16 v[14:17], v[70:73], v[18:21], v[14:17]
	ds_read_b128 v[18:21], v150 offset:3648
	ds_read_b128 v[70:73], v97 offset:7840
	s_waitcnt lgkmcnt(1)
	v_mfma_f32_16x16x32_bf16 v[22:25], v[74:77], v[18:21], v[22:25]
	v_mfma_f32_16x16x32_bf16 v[26:29], v[78:81], v[18:21], v[26:29]
	v_mfma_f32_16x16x32_bf16 v[30:33], v[82:85], v[18:21], v[30:33]
	v_mfma_f32_16x16x32_bf16 v[34:37], v[50:53], v[18:21], v[34:37]
	v_mfma_f32_16x16x32_bf16 v[38:41], v[54:57], v[18:21], v[38:41]
	v_mfma_f32_16x16x32_bf16 v[42:45], v[58:61], v[18:21], v[42:45]
	v_mfma_f32_16x16x32_bf16 v[46:49], v[62:65], v[18:21], v[46:49]
	v_mfma_f32_16x16x32_bf16 v[18:21], v[66:69], v[18:21], v[14:17]
	ds_read_b128 v[66:69], v150 offset:3712
	s_nop 1
	ds_read_b128 v[14:17], v97 offset:7904
	s_waitcnt lgkmcnt(1)
	v_mfma_f32_16x16x32_bf16 v[22:25], v[70:73], v[66:69], v[22:25]
	v_mfma_f32_16x16x32_bf16 v[26:29], v[74:77], v[66:69], v[26:29]
	v_mfma_f32_16x16x32_bf16 v[30:33], v[78:81], v[66:69], v[30:33]
	v_mfma_f32_16x16x32_bf16 v[34:37], v[82:85], v[66:69], v[34:37]
	v_mfma_f32_16x16x32_bf16 v[38:41], v[50:53], v[66:69], v[38:41]
	v_mfma_f32_16x16x32_bf16 v[42:45], v[54:57], v[66:69], v[42:45]
	v_mfma_f32_16x16x32_bf16 v[46:49], v[58:61], v[66:69], v[46:49]
	v_mfma_f32_16x16x32_bf16 v[62:65], v[62:65], v[66:69], v[18:21]
	ds_read_b128 v[66:69], v150 offset:3776
	s_nop 1
	ds_read_b128 v[18:21], v97 offset:7968
	s_waitcnt lgkmcnt(1)
	v_mfma_f32_16x16x32_bf16 v[58:61], v[58:61], v[66:69], v[62:65]
	s_nop 2
	ds_read_b128 v[62:65], v150 offset:3840
	v_mfma_f32_16x16x32_bf16 v[22:25], v[14:17], v[66:69], v[22:25]
	v_mfma_f32_16x16x32_bf16 v[26:29], v[70:73], v[66:69], v[26:29]
	v_mfma_f32_16x16x32_bf16 v[30:33], v[74:77], v[66:69], v[30:33]
	v_mfma_f32_16x16x32_bf16 v[34:37], v[78:81], v[66:69], v[34:37]
	v_mfma_f32_16x16x32_bf16 v[38:41], v[82:85], v[66:69], v[38:41]
	v_mfma_f32_16x16x32_bf16 v[42:45], v[50:53], v[66:69], v[42:45]
	v_mfma_f32_16x16x32_bf16 v[46:49], v[54:57], v[66:69], v[46:49]
	s_waitcnt lgkmcnt(0)
	v_mfma_f32_16x16x32_bf16 v[66:69], v[18:21], v[62:65], v[22:25]
	s_nop 2
	ds_read_b128 v[22:25], v97 offset:8032
	v_mfma_f32_16x16x32_bf16 v[54:57], v[54:57], v[62:65], v[58:61]
	s_nop 2
	ds_read_b128 v[58:61], v150 offset:3904
	v_mfma_f32_16x16x32_bf16 v[26:29], v[14:17], v[62:65], v[26:29]
	v_mfma_f32_16x16x32_bf16 v[30:33], v[70:73], v[62:65], v[30:33]
	v_mfma_f32_16x16x32_bf16 v[34:37], v[74:77], v[62:65], v[34:37]
	v_mfma_f32_16x16x32_bf16 v[38:41], v[78:81], v[62:65], v[38:41]
	v_mfma_f32_16x16x32_bf16 v[42:45], v[82:85], v[62:65], v[42:45]
	v_mfma_f32_16x16x32_bf16 v[46:49], v[50:53], v[62:65], v[46:49]
	s_waitcnt lgkmcnt(0)
	v_mfma_f32_16x16x32_bf16 v[62:65], v[22:25], v[58:61], v[66:69]
	v_mfma_f32_16x16x32_bf16 v[66:69], v[18:21], v[58:61], v[26:29]
	s_nop 2
	ds_read_b128 v[26:29], v97 offset:8096
	v_mfma_f32_16x16x32_bf16 v[50:53], v[50:53], v[58:61], v[54:57]
	s_nop 2
	ds_read_b128 v[54:57], v150 offset:3968
	v_mfma_f32_16x16x32_bf16 v[30:33], v[14:17], v[58:61], v[30:33]
	v_mfma_f32_16x16x32_bf16 v[34:37], v[70:73], v[58:61], v[34:37]
	v_mfma_f32_16x16x32_bf16 v[38:41], v[74:77], v[58:61], v[38:41]
	v_mfma_f32_16x16x32_bf16 v[42:45], v[78:81], v[58:61], v[42:45]
	v_mfma_f32_16x16x32_bf16 v[46:49], v[82:85], v[58:61], v[46:49]
	s_waitcnt lgkmcnt(0)
	v_mfma_f32_16x16x32_bf16 v[58:61], v[26:29], v[54:57], v[62:65]
	v_mfma_f32_16x16x32_bf16 v[62:65], v[22:25], v[54:57], v[66:69]
	v_mfma_f32_16x16x32_bf16 v[66:69], v[18:21], v[54:57], v[30:33]
	v_mfma_f32_16x16x32_bf16 v[34:37], v[14:17], v[54:57], v[34:37]
	s_nop 1
	ds_read_b128 v[30:33], v97 offset:8160
	v_mfma_f32_16x16x32_bf16 v[38:41], v[70:73], v[54:57], v[38:41]
	v_mfma_f32_16x16x32_bf16 v[42:45], v[74:77], v[54:57], v[42:45]
	v_mfma_f32_16x16x32_bf16 v[46:49], v[78:81], v[54:57], v[46:49]
	v_mfma_f32_16x16x32_bf16 v[50:53], v[82:85], v[54:57], v[50:53]
	ds_read_b128 v[54:57], v150 offset:4032
	s_waitcnt lgkmcnt(0)
	v_mfma_f32_16x16x32_bf16 v[82:85], v[70:73], v[54:57], v[42:45]
	s_nop 2
	ds_read_b128 v[42:45], v97 offset:8224
	v_mfma_f32_16x16x32_bf16 v[50:53], v[78:81], v[54:57], v[50:53]
	ds_read_b128 v[78:81], v150 offset:4096
	v_mfma_f32_16x16x32_bf16 v[58:61], v[30:33], v[54:57], v[58:61]
	v_mfma_f32_16x16x32_bf16 v[62:65], v[26:29], v[54:57], v[62:65]
	v_mfma_f32_16x16x32_bf16 v[66:69], v[22:25], v[54:57], v[66:69]
	v_mfma_f32_16x16x32_bf16 v[34:37], v[18:21], v[54:57], v[34:37]
	v_mfma_f32_16x16x32_bf16 v[38:41], v[14:17], v[54:57], v[38:41]
	v_mfma_f32_16x16x32_bf16 v[46:49], v[74:77], v[54:57], v[46:49]
	ds_read_b128 v[54:57], v97 offset:8288
	s_waitcnt lgkmcnt(1)
	v_mfma_f32_16x16x32_bf16 v[58:61], v[42:45], v[78:81], v[58:61]
	v_mfma_f32_16x16x32_bf16 v[140:143], v[30:33], v[78:81], v[62:65]
	v_mfma_f32_16x16x32_bf16 v[144:147], v[26:29], v[78:81], v[66:69]
	v_mfma_f32_16x16x32_bf16 v[34:37], v[22:25], v[78:81], v[34:37]
	v_mfma_f32_16x16x32_bf16 v[38:41], v[18:21], v[78:81], v[38:41]
	v_mfma_f32_16x16x32_bf16 v[82:85], v[14:17], v[78:81], v[82:85]
	v_mfma_f32_16x16x32_bf16 v[190:193], v[70:73], v[78:81], v[46:49]
	v_mfma_f32_16x16x32_bf16 v[74:77], v[74:77], v[78:81], v[50:53]
	ds_read_b128 v[78:81], v150 offset:4160
	s_waitcnt lgkmcnt(0)
	v_mfma_f32_16x16x32_bf16 v[70:73], v[70:73], v[78:81], v[74:77]
	s_nop 4
	ds_read_b128 v[74:77], v150 offset:4224
	v_mfma_f32_16x16x32_bf16 v[50:53], v[26:29], v[78:81], v[34:37]
	v_mfma_f32_16x16x32_bf16 v[46:49], v[22:25], v[78:81], v[38:41]
	v_mfma_f32_16x16x32_bf16 v[38:41], v[18:21], v[78:81], v[82:85]
	s_nop 2
	ds_read_b128 v[82:85], v97 offset:8352
	v_mfma_f32_16x16x32_bf16 v[62:65], v[54:57], v[78:81], v[58:61]
	v_mfma_f32_16x16x32_bf16 v[58:61], v[30:33], v[78:81], v[144:147]
	s_waitcnt lgkmcnt(1)
	v_mfma_f32_16x16x32_bf16 v[30:33], v[30:33], v[74:77], v[50:53]
	s_nop 0
	v_mov_b32_e32 v147, 0
	s_nop 0
	v_lshl_add_u64 v[50:51], s[42:43], 0, v[134:135]
	v_mfma_f32_16x16x32_bf16 v[26:29], v[26:29], v[74:77], v[46:49]
	v_mov_b32_e32 v135, 0
	s_nop 1
	v_lshl_add_u64 v[46:47], v[98:99], 1, v[50:51]
	v_add_co_u32_e32 v48, vcc, 0x4000, v46
	v_mfma_f32_16x16x32_bf16 v[66:69], v[42:45], v[78:81], v[140:143]
	s_nop 0
	v_addc_co_u32_e32 v49, vcc, 0, v47, vcc
	global_load_dwordx2 v[144:145], v[48:49], off
	v_mfma_f32_16x16x32_bf16 v[34:37], v[14:17], v[78:81], v[190:193]
	s_waitcnt lgkmcnt(0)
	v_mfma_f32_16x16x32_bf16 v[62:65], v[82:85], v[74:77], v[62:65]
	v_mfma_f32_16x16x32_bf16 v[54:57], v[54:57], v[74:77], v[66:69]
	v_mfma_f32_16x16x32_bf16 v[42:45], v[42:45], v[74:77], v[58:61]
	v_mfma_f32_16x16x32_bf16 v[22:25], v[22:25], v[74:77], v[38:41]
	v_mfma_f32_16x16x32_bf16 v[18:21], v[18:21], v[74:77], v[34:37]
	v_mfma_f32_16x16x32_bf16 v[14:17], v[14:17], v[74:77], v[70:73]
	s_nop 1
	v_lshl_add_u64 v[34:35], v[46:47], 0, s[16:17]
	s_mov_b64 s[4:5], exec
	v_readlane_b32 s6, v255, 37
	v_readlane_b32 s7, v255, 38
	s_and_b64 s[6:7], s[4:5], s[6:7]
	s_mov_b64 exec, s[6:7]
	s_cbranch_execz .LBB0_868
	global_load_short_d16_hi v147, v[34:35], off offset:-2
